# GEMM load segments: the 10 M0-hazard s_nop slots per iteration filled with deferred ds_read_b128 (pure reorder)
# speedup vs baseline: 1.0070x; 1.0005x over previous
; #define PG8_STAGE(bufoff, gbase, voff) do { _Pragma("unroll") for (int _i = 0; _i < 2; ++_i) \
;         __builtin_amdgcn_global_load_lds((const unsigned*)((const char*)(gbase) + (voff)[_i]), (PG8_LAS unsigned*)(lds + (bufoff) + ldsw + _i * 8192), 16, 0, 0); } while (0)
; #define PG8_LDA(dst, b, h) do { _Pragma("unroll") for (int m = 0; m < 4; ++m) _Pragma("unroll") for (int k = 0; k < 2; ++k) dst[m][k] = *(const PG8_LAS bf16x8*)(lds + PG8_SA(b, h) + aoff + m * 2048 + k * 1024); } while (0)
; #define PG8_LDB(dst, b, h) do { _Pragma("unroll") for (int n = 0; n < 2; ++n) _Pragma("unroll") for (int k = 0; k < 2; ++k) dst[n][k] = *(const PG8_LAS bf16x8*)(lds + PG8_SB(b, h) + boff + n * 2048 + k * 1024); } while (0)
; #define PG8_SCHED __builtin_amdgcn_sched_barrier(0)
; template <class Epi, class Sched, bool ALIGN_EPI = false, bool SP2 = false>
; __device__ __forceinline__ void gemm_phase(PG8_LAS unsigned char* lds, const Gemm g, const Sched& S, const Epi& E) {
;     ...
;             const char* a1 = cA + (size_t)(t + 1) * kstep;
;             const char* a2 = last ? nA : cA + (size_t)(t + 2) * kstep; const char* b2 = last ? nB : cB + (size_t)(t + 2) * kstep;
;             const char* a3 = a2 + kstep; const char* b3 = b2 + kstep;
;             if (last && has_next) S.a_ready(nxt);
;             if constexpr (SP2) {
;             PG8_LDB(B0, 0, 0); PG8_LDB(B1, 0, 1); PG8_SCHED; PG8_LDA(At, 0, 0); PG8_STAGE(PG8_SA(1, 1), a1 + hstep, voffA);
.LBB0_25:
	s_add_i32 s88, 0, 0x10000
	s_add_i32 s90, 0, 0x14000
	ds_read_b128 v[142:145], v200
	ds_read_b128 v[146:149], v200 offset:1024
	ds_read_b128 v[150:153], v200 offset:2048
	ds_read_b128 v[154:157], v200 offset:3072
	ds_read_b128 v[164:167], v200 offset:16384
	ds_read_b128 v[168:171], v200 offset:17408
	ds_read_b128 v[172:175], v200 offset:18432
	ds_read_b128 v[176:179], v200 offset:19456
	s_add_i32 m0, s29, 0xc000
	ds_read_b128 v[180:183], v141
	ds_read_b128 v[184:187], v141 offset:1024
	ds_read_b128 v[188:191], v141 offset:2048
	ds_read_b128 v[192:195], v141 offset:3072
	ds_read_b128 v[196:199], v141 offset:4096
	ds_read_b128 v[222:225], v141 offset:5120
	ds_read_b128 v[226:229], v141 offset:6144
	global_load_lds_dwordx4 v134, s[80:81]
	s_add_i32 m0, s29, 0xe000
	ds_read_b128 v[230:233], v141 offset:7168
	global_load_lds_dwordx4 v136, s[80:81]
	s_add_u32 s4, s80, 0xfff80080
	s_addc_u32 s5, s81, -1
	s_cmp_eq_u32 s87, 28
	s_cselect_b32 s53, s55, s5
	s_cselect_b32 s52, s83, s4
	s_cselect_b32 s5, s73, s86
	s_cselect_b32 s4, s84, s85

; #define PG8_STAGE(bufoff, gbase, voff) do { _Pragma("unroll") for (int _i = 0; _i < 2; ++_i) \
;         __builtin_amdgcn_global_load_lds((const unsigned*)((const char*)(gbase) + (voff)[_i]), (PG8_LAS unsigned*)(lds + (bufoff) + ldsw + _i * 8192), 16, 0, 0); } while (0)
; #define PG8_LDA(dst, b, h) do { _Pragma("unroll") for (int m = 0; m < 4; ++m) _Pragma("unroll") for (int k = 0; k < 2; ++k) dst[m][k] = *(const PG8_LAS bf16x8*)(lds + PG8_SA(b, h) + aoff + m * 2048 + k * 1024); } while (0)
; #define PG8_MMA(ai, bj, At, Bt) do { __builtin_amdgcn_s_setprio(1); _Pragma("unroll") for (int m = 0; m < 4; ++m) _Pragma("unroll") for (int n = 0; n < 2; ++n) _Pragma("unroll") for (int k = 0; k < 2; ++k) \
;         acc[ai][bj][m][n] = __builtin_amdgcn_mfma_f32_16x16x32_bf16(Bt[n][k], At[m][k], acc[ai][bj][m][n], 0, 0, 0); __builtin_amdgcn_s_setprio(0); } while (0)
; #define PG8_WAIT_V(n) asm volatile("s_waitcnt vmcnt(" #n ")" ::: "memory")
; #define PG8_WAIT_L(n) asm volatile("s_waitcnt lgkmcnt(" #n ")" ::: "memory")
; #define PG8_BAR __builtin_amdgcn_s_barrier()
; #define PG8_SCHED __builtin_amdgcn_sched_barrier(0)
; template <class Epi, class Sched, bool ALIGN_EPI = false, bool SP2 = false>
; __device__ __forceinline__ void gemm_phase(PG8_LAS unsigned char* lds, const Gemm g, const Sched& S, const Epi& E) {
;     ...
;             PG8_WAIT_V(8); PG8_WAIT_L(0); PG8_BAR; PG8_MMA(0, 0, At, B0); PG8_MMA(0, 1, At, B1); PG8_BAR; PG8_SCHED;
;             PG8_LDA(At, 0, 1); PG8_STAGE(PG8_SB(0, 0), b2, voffB); PG8_STAGE(PG8_SB(0, 1), b2 + hstep, voffB); PG8_STAGE(PG8_SA(0, 0), a2, voffA);
	s_waitcnt vmcnt(8)
	s_waitcnt lgkmcnt(0)
	s_barrier
	s_waitcnt lgkmcnt(0)
	v_mfma_f32_16x16x32_bf16 v[124:127], v[142:145], v[180:183], v[124:127]
	v_mfma_f32_16x16x32_bf16 v[120:123], v[150:153], v[180:183], v[120:123]
	v_mfma_f32_16x16x32_bf16 v[116:119], v[142:145], v[188:191], v[116:119]
	v_mfma_f32_16x16x32_bf16 v[112:115], v[150:153], v[188:191], v[112:115]
	v_mfma_f32_16x16x32_bf16 v[100:103], v[142:145], v[196:199], v[100:103]
	v_mfma_f32_16x16x32_bf16 v[96:99], v[150:153], v[196:199], v[96:99]
	v_mfma_f32_16x16x32_bf16 v[84:87], v[142:145], v[226:229], v[84:87]
	v_mfma_f32_16x16x32_bf16 v[80:83], v[150:153], v[226:229], v[80:83]
	v_mfma_f32_16x16x32_bf16 v[124:127], v[146:149], v[184:187], v[124:127]
	v_mfma_f32_16x16x32_bf16 v[120:123], v[154:157], v[184:187], v[120:123]
	v_mfma_f32_16x16x32_bf16 v[116:119], v[146:149], v[192:195], v[116:119]
	v_mfma_f32_16x16x32_bf16 v[112:115], v[154:157], v[192:195], v[112:115]
	v_mfma_f32_16x16x32_bf16 v[100:103], v[146:149], v[222:225], v[100:103]
	v_mfma_f32_16x16x32_bf16 v[96:99], v[154:157], v[222:225], v[96:99]
	v_mfma_f32_16x16x32_bf16 v[84:87], v[146:149], v[230:233], v[84:87]
	v_mfma_f32_16x16x32_bf16 v[80:83], v[154:157], v[230:233], v[80:83]
	v_mfma_f32_16x16x32_bf16 v[108:111], v[164:167], v[180:183], v[108:111]
	v_mfma_f32_16x16x32_bf16 v[104:107], v[172:175], v[180:183], v[104:107]
	v_mfma_f32_16x16x32_bf16 v[92:95], v[164:167], v[188:191], v[92:95]
	v_mfma_f32_16x16x32_bf16 v[88:91], v[172:175], v[188:191], v[88:91]
	v_mfma_f32_16x16x32_bf16 v[76:79], v[164:167], v[196:199], v[76:79]
	v_mfma_f32_16x16x32_bf16 v[72:75], v[172:175], v[196:199], v[72:75]
	v_mfma_f32_16x16x32_bf16 v[68:71], v[164:167], v[226:229], v[68:71]
	v_mfma_f32_16x16x32_bf16 v[64:67], v[172:175], v[226:229], v[64:67]
	v_mfma_f32_16x16x32_bf16 v[108:111], v[168:171], v[184:187], v[108:111]
	v_mfma_f32_16x16x32_bf16 v[104:107], v[176:179], v[184:187], v[104:107]
	v_mfma_f32_16x16x32_bf16 v[92:95], v[168:171], v[192:195], v[92:95]
	v_mfma_f32_16x16x32_bf16 v[88:91], v[176:179], v[192:195], v[88:91]
	v_mfma_f32_16x16x32_bf16 v[76:79], v[168:171], v[222:225], v[76:79]
	v_mfma_f32_16x16x32_bf16 v[72:75], v[176:179], v[222:225], v[72:75]
	v_mfma_f32_16x16x32_bf16 v[68:71], v[168:171], v[230:233], v[68:71]
	v_mfma_f32_16x16x32_bf16 v[64:67], v[176:179], v[230:233], v[64:67]
	s_barrier
	s_add_i32 s88, s88, s28
	s_mov_b32 m0, s88
	ds_read_b128 v[180:183], v141 offset:16384
	ds_read_b128 v[184:187], v141 offset:17408
	ds_read_b128 v[188:191], v141 offset:18432
	ds_read_b128 v[192:195], v141 offset:19456
	global_load_lds_dwordx4 v160, s[4:5]
	s_add_i32 m0, s88, 0x2000
	s_add_u32 s88, s4, 0x80000
	s_addc_u32 s89, s5, 0
	s_add_i32 s90, s90, s28
	global_load_lds_dwordx4 v128, s[4:5]
	s_mov_b32 m0, s90
	ds_read_b128 v[196:199], v141 offset:20480
	global_load_lds_dwordx4 v160, s[88:89]
	s_add_i32 m0, s90, 0x2000
	ds_read_b128 v[222:225], v141 offset:21504
	global_load_lds_dwordx4 v128, s[88:89]
	s_mov_b32 m0, s29
	ds_read_b128 v[226:229], v141 offset:22528
	global_load_lds_dwordx4 v132, s[52:53]
	s_mov_b32 m0, s45
	ds_read_b128 v[230:233], v141 offset:23552
	global_load_lds_dwordx4 v130, s[52:53]
	s_add_u32 s98, s52, 0x80
	s_addc_u32 s99, s53, 0


; #define PG8_STAGE(bufoff, gbase, voff) do { _Pragma("unroll") for (int _i = 0; _i < 2; ++_i) \
;         __builtin_amdgcn_global_load_lds((const unsigned*)((const char*)(gbase) + (voff)[_i]), (PG8_LAS unsigned*)(lds + (bufoff) + ldsw + _i * 8192), 16, 0, 0); } while (0)
; #define PG8_LDA(dst, b, h) do { _Pragma("unroll") for (int m = 0; m < 4; ++m) _Pragma("unroll") for (int k = 0; k < 2; ++k) dst[m][k] = *(const PG8_LAS bf16x8*)(lds + PG8_SA(b, h) + aoff + m * 2048 + k * 1024); } while (0)
; #define PG8_LDB(dst, b, h) do { _Pragma("unroll") for (int n = 0; n < 2; ++n) _Pragma("unroll") for (int k = 0; k < 2; ++k) dst[n][k] = *(const PG8_LAS bf16x8*)(lds + PG8_SB(b, h) + boff + n * 2048 + k * 1024); } while (0)
; #define PG8_MMA(ai, bj, At, Bt) do { __builtin_amdgcn_s_setprio(1); _Pragma("unroll") for (int m = 0; m < 4; ++m) _Pragma("unroll") for (int n = 0; n < 2; ++n) _Pragma("unroll") for (int k = 0; k < 2; ++k) \
;         acc[ai][bj][m][n] = __builtin_amdgcn_mfma_f32_16x16x32_bf16(Bt[n][k], At[m][k], acc[ai][bj][m][n], 0, 0, 0); __builtin_amdgcn_s_setprio(0); } while (0)
; #define PG8_WAIT_V(n) asm volatile("s_waitcnt vmcnt(" #n ")" ::: "memory")
; #define PG8_WAIT_L(n) asm volatile("s_waitcnt lgkmcnt(" #n ")" ::: "memory")
; #define PG8_BAR __builtin_amdgcn_s_barrier()
; #define PG8_SCHED __builtin_amdgcn_sched_barrier(0)
; template <class Epi, class Sched, bool ALIGN_EPI = false, bool SP2 = false>
; __device__ __forceinline__ void gemm_phase(PG8_LAS unsigned char* lds, const Gemm g, const Sched& S, const Epi& E) {
;     ...
;             PG8_WAIT_V(8); PG8_WAIT_L(0); PG8_BAR; PG8_MMA(1, 0, At, B0); PG8_MMA(1, 1, At, B1); PG8_BAR; PG8_SCHED;
;             PG8_LDB(B0, 1, 0); PG8_LDB(B1, 1, 1); PG8_SCHED; PG8_LDA(At, 1, 0); PG8_STAGE(PG8_SA(0, 1), a2 + hstep, voffA);
	s_waitcnt vmcnt(8)
	s_waitcnt lgkmcnt(0)
	s_barrier
	s_waitcnt lgkmcnt(0)
	v_mfma_f32_16x16x32_bf16 v[60:63], v[142:145], v[180:183], v[60:63]
	v_mfma_f32_16x16x32_bf16 v[56:59], v[150:153], v[180:183], v[56:59]
	v_mfma_f32_16x16x32_bf16 v[52:55], v[142:145], v[188:191], v[52:55]
	v_mfma_f32_16x16x32_bf16 v[48:51], v[150:153], v[188:191], v[48:51]
	v_mfma_f32_16x16x32_bf16 v[36:39], v[142:145], v[196:199], v[36:39]
	v_mfma_f32_16x16x32_bf16 v[32:35], v[150:153], v[196:199], v[32:35]
	v_mfma_f32_16x16x32_bf16 v[20:23], v[142:145], v[226:229], v[20:23]
	v_mfma_f32_16x16x32_bf16 v[16:19], v[150:153], v[226:229], v[16:19]
	v_mfma_f32_16x16x32_bf16 v[60:63], v[146:149], v[184:187], v[60:63]
	v_mfma_f32_16x16x32_bf16 v[56:59], v[154:157], v[184:187], v[56:59]
	v_mfma_f32_16x16x32_bf16 v[52:55], v[146:149], v[192:195], v[52:55]
	v_mfma_f32_16x16x32_bf16 v[48:51], v[154:157], v[192:195], v[48:51]
	v_mfma_f32_16x16x32_bf16 v[36:39], v[146:149], v[222:225], v[36:39]
	v_mfma_f32_16x16x32_bf16 v[32:35], v[154:157], v[222:225], v[32:35]
	v_mfma_f32_16x16x32_bf16 v[20:23], v[146:149], v[230:233], v[20:23]
	v_mfma_f32_16x16x32_bf16 v[16:19], v[154:157], v[230:233], v[16:19]
	v_mfma_f32_16x16x32_bf16 v[44:47], v[164:167], v[180:183], v[44:47]
	v_mfma_f32_16x16x32_bf16 v[40:43], v[172:175], v[180:183], v[40:43]
	v_mfma_f32_16x16x32_bf16 v[28:31], v[164:167], v[188:191], v[28:31]
	v_mfma_f32_16x16x32_bf16 v[24:27], v[172:175], v[188:191], v[24:27]
	v_mfma_f32_16x16x32_bf16 v[12:15], v[164:167], v[196:199], v[12:15]
	v_mfma_f32_16x16x32_bf16 v[8:11], v[172:175], v[196:199], v[8:11]
	v_mfma_f32_16x16x32_bf16 v[4:7], v[164:167], v[226:229], v[4:7]
	v_mfma_f32_16x16x32_bf16 v[0:3], v[172:175], v[226:229], v[0:3]
	v_mfma_f32_16x16x32_bf16 v[44:47], v[168:171], v[184:187], v[44:47]
	v_mfma_f32_16x16x32_bf16 v[40:43], v[176:179], v[184:187], v[40:43]
	v_mfma_f32_16x16x32_bf16 v[28:31], v[168:171], v[192:195], v[28:31]
	v_mfma_f32_16x16x32_bf16 v[24:27], v[176:179], v[192:195], v[24:27]
	v_mfma_f32_16x16x32_bf16 v[12:15], v[168:171], v[222:225], v[12:15]
	v_mfma_f32_16x16x32_bf16 v[8:11], v[176:179], v[222:225], v[8:11]
	v_mfma_f32_16x16x32_bf16 v[4:7], v[168:171], v[230:233], v[4:7]
	v_mfma_f32_16x16x32_bf16 v[0:3], v[176:179], v[230:233], v[0:3]
	s_barrier
	s_add_i32 s88, 0, 0x18000
	s_add_i32 s89, 0, 0x1c000
	ds_read_b128 v[142:145], v200 offset:32768
	ds_read_b128 v[146:149], v200 offset:33792
	ds_read_b128 v[150:153], v200 offset:34816
	ds_read_b128 v[154:157], v200 offset:35840
	ds_read_b128 v[164:167], v200 offset:49152
	ds_read_b128 v[168:171], v200 offset:50176
	ds_read_b128 v[172:175], v200 offset:51200
	ds_read_b128 v[176:179], v200 offset:52224
	s_add_u32 s52, s52, 0x80000
	s_addc_u32 s53, s53, 0
	s_mov_b32 m0, s56
	ds_read_b128 v[180:183], v141 offset:32768
	ds_read_b128 v[184:187], v141 offset:33792
	ds_read_b128 v[188:191], v141 offset:34816
	ds_read_b128 v[192:195], v141 offset:35840
	ds_read_b128 v[196:199], v141 offset:36864
	ds_read_b128 v[222:225], v141 offset:37888
	ds_read_b128 v[226:229], v141 offset:38912
	global_load_lds_dwordx4 v132, s[52:53]
	s_mov_b32 m0, s57
	ds_read_b128 v[230:233], v141 offset:39936
	global_load_lds_dwordx4 v130, s[52:53]

; #define PG8_STAGE(bufoff, gbase, voff) do { _Pragma("unroll") for (int _i = 0; _i < 2; ++_i) \
;         __builtin_amdgcn_global_load_lds((const unsigned*)((const char*)(gbase) + (voff)[_i]), (PG8_LAS unsigned*)(lds + (bufoff) + ldsw + _i * 8192), 16, 0, 0); } while (0)
; #define PG8_LDA(dst, b, h) do { _Pragma("unroll") for (int m = 0; m < 4; ++m) _Pragma("unroll") for (int k = 0; k < 2; ++k) dst[m][k] = *(const PG8_LAS bf16x8*)(lds + PG8_SA(b, h) + aoff + m * 2048 + k * 1024); } while (0)
; #define PG8_MMA(ai, bj, At, Bt) do { __builtin_amdgcn_s_setprio(1); _Pragma("unroll") for (int m = 0; m < 4; ++m) _Pragma("unroll") for (int n = 0; n < 2; ++n) _Pragma("unroll") for (int k = 0; k < 2; ++k) \
;         acc[ai][bj][m][n] = __builtin_amdgcn_mfma_f32_16x16x32_bf16(Bt[n][k], At[m][k], acc[ai][bj][m][n], 0, 0, 0); __builtin_amdgcn_s_setprio(0); } while (0)
; #define PG8_WAIT_V(n) asm volatile("s_waitcnt vmcnt(" #n ")" ::: "memory")
; #define PG8_WAIT_L(n) asm volatile("s_waitcnt lgkmcnt(" #n ")" ::: "memory")
; #define PG8_BAR __builtin_amdgcn_s_barrier()
; #define PG8_SCHED __builtin_amdgcn_sched_barrier(0)
; template <class Epi, class Sched, bool ALIGN_EPI = false, bool SP2 = false>
; __device__ __forceinline__ void gemm_phase(PG8_LAS unsigned char* lds, const Gemm g, const Sched& S, const Epi& E) {
;     ...
;             PG8_WAIT_V(8); PG8_WAIT_L(0); PG8_BAR; PG8_MMA(0, 0, At, B0); PG8_MMA(0, 1, At, B1); PG8_BAR; PG8_SCHED;
;             PG8_LDA(At, 1, 1); PG8_STAGE(PG8_SB(1, 0), b3, voffB); PG8_STAGE(PG8_SB(1, 1), b3 + hstep, voffB); PG8_STAGE(PG8_SA(1, 0), a3, voffA);
	s_waitcnt vmcnt(8)
	s_waitcnt lgkmcnt(0)
	s_barrier
	s_waitcnt lgkmcnt(0)
	v_mfma_f32_16x16x32_bf16 v[124:127], v[142:145], v[180:183], v[124:127]
	v_mfma_f32_16x16x32_bf16 v[120:123], v[150:153], v[180:183], v[120:123]
	v_mfma_f32_16x16x32_bf16 v[116:119], v[142:145], v[188:191], v[116:119]
	v_mfma_f32_16x16x32_bf16 v[112:115], v[150:153], v[188:191], v[112:115]
	v_mfma_f32_16x16x32_bf16 v[100:103], v[142:145], v[196:199], v[100:103]
	v_mfma_f32_16x16x32_bf16 v[96:99], v[150:153], v[196:199], v[96:99]
	v_mfma_f32_16x16x32_bf16 v[84:87], v[142:145], v[226:229], v[84:87]
	v_mfma_f32_16x16x32_bf16 v[80:83], v[150:153], v[226:229], v[80:83]
	v_mfma_f32_16x16x32_bf16 v[124:127], v[146:149], v[184:187], v[124:127]
	v_mfma_f32_16x16x32_bf16 v[120:123], v[154:157], v[184:187], v[120:123]
	v_mfma_f32_16x16x32_bf16 v[116:119], v[146:149], v[192:195], v[116:119]
	v_mfma_f32_16x16x32_bf16 v[112:115], v[154:157], v[192:195], v[112:115]
	v_mfma_f32_16x16x32_bf16 v[100:103], v[146:149], v[222:225], v[100:103]
	v_mfma_f32_16x16x32_bf16 v[96:99], v[154:157], v[222:225], v[96:99]
	v_mfma_f32_16x16x32_bf16 v[84:87], v[146:149], v[230:233], v[84:87]
	v_mfma_f32_16x16x32_bf16 v[80:83], v[154:157], v[230:233], v[80:83]
	v_mfma_f32_16x16x32_bf16 v[108:111], v[164:167], v[180:183], v[108:111]
	v_mfma_f32_16x16x32_bf16 v[104:107], v[172:175], v[180:183], v[104:107]
	v_mfma_f32_16x16x32_bf16 v[92:95], v[164:167], v[188:191], v[92:95]
	v_mfma_f32_16x16x32_bf16 v[88:91], v[172:175], v[188:191], v[88:91]
	v_mfma_f32_16x16x32_bf16 v[76:79], v[164:167], v[196:199], v[76:79]
	v_mfma_f32_16x16x32_bf16 v[72:75], v[172:175], v[196:199], v[72:75]
	v_mfma_f32_16x16x32_bf16 v[68:71], v[164:167], v[226:229], v[68:71]
	v_mfma_f32_16x16x32_bf16 v[64:67], v[172:175], v[226:229], v[64:67]
	v_mfma_f32_16x16x32_bf16 v[108:111], v[168:171], v[184:187], v[108:111]
	v_mfma_f32_16x16x32_bf16 v[104:107], v[176:179], v[184:187], v[104:107]
	v_mfma_f32_16x16x32_bf16 v[92:95], v[168:171], v[192:195], v[92:95]
	v_mfma_f32_16x16x32_bf16 v[88:91], v[176:179], v[192:195], v[88:91]
	v_mfma_f32_16x16x32_bf16 v[76:79], v[168:171], v[222:225], v[76:79]
	v_mfma_f32_16x16x32_bf16 v[72:75], v[176:179], v[222:225], v[72:75]
	v_mfma_f32_16x16x32_bf16 v[68:71], v[168:171], v[230:233], v[68:71]
	v_mfma_f32_16x16x32_bf16 v[64:67], v[176:179], v[230:233], v[64:67]
	s_barrier
	s_add_i32 s52, s88, s28
	s_mov_b32 m0, s52
	ds_read_b128 v[180:183], v141 offset:49152
	ds_read_b128 v[184:187], v141 offset:50176
	ds_read_b128 v[188:191], v141 offset:51200
	ds_read_b128 v[192:195], v141 offset:52224
	s_add_u32 s4, s4, 0x80
	s_addc_u32 s5, s5, 0
	global_load_lds_dwordx4 v160, s[4:5]
	s_add_i32 m0, s52, 0x2000
	s_add_i32 s52, s89, s28
	global_load_lds_dwordx4 v128, s[4:5]
	s_add_u32 s4, s4, 0x80000
	s_addc_u32 s5, s5, 0
	s_mov_b32 m0, s52
	ds_read_b128 v[196:199], v141 offset:53248
	global_load_lds_dwordx4 v160, s[4:5]
	s_add_i32 m0, s52, 0x2000
	ds_read_b128 v[222:225], v141 offset:54272
	global_load_lds_dwordx4 v128, s[4:5]
	s_mov_b32 m0, s24
	ds_read_b128 v[226:229], v141 offset:55296
	global_load_lds_dwordx4 v132, s[98:99]
	s_mov_b32 m0, s59
	ds_read_b128 v[230:233], v141 offset:56320
	global_load_lds_dwordx4 v130, s[98:99]


; #define PG8_MMA(ai, bj, At, Bt) do { __builtin_amdgcn_s_setprio(1); _Pragma("unroll") for (int m = 0; m < 4; ++m) _Pragma("unroll") for (int n = 0; n < 2; ++n) _Pragma("unroll") for (int k = 0; k < 2; ++k) \
;         acc[ai][bj][m][n] = __builtin_amdgcn_mfma_f32_16x16x32_bf16(Bt[n][k], At[m][k], acc[ai][bj][m][n], 0, 0, 0); __builtin_amdgcn_s_setprio(0); } while (0)
; #define PG8_WAIT_V(n) asm volatile("s_waitcnt vmcnt(" #n ")" ::: "memory")
; #define PG8_WAIT_L(n) asm volatile("s_waitcnt lgkmcnt(" #n ")" ::: "memory")
; #define PG8_BAR __builtin_amdgcn_s_barrier()
; #define PG8_SCHED __builtin_amdgcn_sched_barrier(0)
; template <class Epi, class Sched, bool ALIGN_EPI = false, bool SP2 = false>
; __device__ __forceinline__ void gemm_phase(PG8_LAS unsigned char* lds, const Gemm g, const Sched& S, const Epi& E) {
;     ...
;         for (int t = 0; t < nt; t += 2) {
;     ...
;             PG8_WAIT_V(8); PG8_WAIT_L(0); PG8_BAR; PG8_MMA(1, 0, At, B0); PG8_MMA(1, 1, At, B1); PG8_BAR; PG8_SCHED;
	s_waitcnt vmcnt(8)
	s_waitcnt lgkmcnt(0)
	s_barrier
	s_waitcnt lgkmcnt(0)
	v_mfma_f32_16x16x32_bf16 v[60:63], v[142:145], v[180:183], v[60:63]
	v_mfma_f32_16x16x32_bf16 v[56:59], v[150:153], v[180:183], v[56:59]
	v_mfma_f32_16x16x32_bf16 v[52:55], v[142:145], v[188:191], v[52:55]
	v_mfma_f32_16x16x32_bf16 v[48:51], v[150:153], v[188:191], v[48:51]
	v_mfma_f32_16x16x32_bf16 v[36:39], v[142:145], v[196:199], v[36:39]
	v_mfma_f32_16x16x32_bf16 v[32:35], v[150:153], v[196:199], v[32:35]
	v_mfma_f32_16x16x32_bf16 v[20:23], v[142:145], v[226:229], v[20:23]
	v_mfma_f32_16x16x32_bf16 v[16:19], v[150:153], v[226:229], v[16:19]
	v_mfma_f32_16x16x32_bf16 v[60:63], v[146:149], v[184:187], v[60:63]
	v_mfma_f32_16x16x32_bf16 v[56:59], v[154:157], v[184:187], v[56:59]
	v_mfma_f32_16x16x32_bf16 v[52:55], v[146:149], v[192:195], v[52:55]
	v_mfma_f32_16x16x32_bf16 v[48:51], v[154:157], v[192:195], v[48:51]
	v_mfma_f32_16x16x32_bf16 v[36:39], v[146:149], v[222:225], v[36:39]
	v_mfma_f32_16x16x32_bf16 v[32:35], v[154:157], v[222:225], v[32:35]
	v_mfma_f32_16x16x32_bf16 v[20:23], v[146:149], v[230:233], v[20:23]
	v_mfma_f32_16x16x32_bf16 v[16:19], v[154:157], v[230:233], v[16:19]
	v_mfma_f32_16x16x32_bf16 v[44:47], v[164:167], v[180:183], v[44:47]
	v_mfma_f32_16x16x32_bf16 v[40:43], v[172:175], v[180:183], v[40:43]
	v_mfma_f32_16x16x32_bf16 v[28:31], v[164:167], v[188:191], v[28:31]
	v_mfma_f32_16x16x32_bf16 v[24:27], v[172:175], v[188:191], v[24:27]
	v_mfma_f32_16x16x32_bf16 v[12:15], v[164:167], v[196:199], v[12:15]
	v_mfma_f32_16x16x32_bf16 v[8:11], v[172:175], v[196:199], v[8:11]
	v_mfma_f32_16x16x32_bf16 v[4:7], v[164:167], v[226:229], v[4:7]
	v_mfma_f32_16x16x32_bf16 v[0:3], v[172:175], v[226:229], v[0:3]
	v_mfma_f32_16x16x32_bf16 v[44:47], v[168:171], v[184:187], v[44:47]
	v_mfma_f32_16x16x32_bf16 v[40:43], v[176:179], v[184:187], v[40:43]
	v_mfma_f32_16x16x32_bf16 v[28:31], v[168:171], v[192:195], v[28:31]
	v_mfma_f32_16x16x32_bf16 v[24:27], v[176:179], v[192:195], v[24:27]
	v_mfma_f32_16x16x32_bf16 v[12:15], v[168:171], v[222:225], v[12:15]
	v_mfma_f32_16x16x32_bf16 v[8:11], v[176:179], v[222:225], v[8:11]
	v_mfma_f32_16x16x32_bf16 v[4:7], v[168:171], v[230:233], v[4:7]
	v_mfma_f32_16x16x32_bf16 v[0:3], v[176:179], v[230:233], v[0:3]
	s_barrier
	s_add_i32 s87, s87, 2
	s_add_u32 s80, s80, 0x100
	s_addc_u32 s81, s81, 0
	s_add_u32 s85, s85, 0x100
	s_addc_u32 s86, s86, 0
	s_cmp_gt_u32 s87, 29
	s_cbranch_scc0 .LBB0_25
	s_and_b64 vcc, exec, s[42:43]
	s_cbranch_vccz .LBB0_28
	s_barrier

; #define PG8_STAGE(bufoff, gbase, voff) do { _Pragma("unroll") for (int _i = 0; _i < 2; ++_i) \
;         __builtin_amdgcn_global_load_lds((const unsigned*)((const char*)(gbase) + (voff)[_i]), (PG8_LAS unsigned*)(lds + (bufoff) + ldsw + _i * 8192), 16, 0, 0); } while (0)
; #define PG8_LDA(dst, b, h) do { _Pragma("unroll") for (int m = 0; m < 4; ++m) _Pragma("unroll") for (int k = 0; k < 2; ++k) dst[m][k] = *(const PG8_LAS bf16x8*)(lds + PG8_SA(b, h) + aoff + m * 2048 + k * 1024); } while (0)
; #define PG8_LDB(dst, b, h) do { _Pragma("unroll") for (int n = 0; n < 2; ++n) _Pragma("unroll") for (int k = 0; k < 2; ++k) dst[n][k] = *(const PG8_LAS bf16x8*)(lds + PG8_SB(b, h) + boff + n * 2048 + k * 1024); } while (0)
; #define PG8_SCHED __builtin_amdgcn_sched_barrier(0)
; template <class Epi, class Sched, bool ALIGN_EPI = false, bool SP2 = false>
; __device__ __forceinline__ void gemm_phase(PG8_LAS unsigned char* lds, const Gemm g, const Sched& S, const Epi& E) {
;     ...
;             const char* a1 = cA + (size_t)(t + 1) * kstep;
;             const char* a2 = last ? nA : cA + (size_t)(t + 2) * kstep; const char* b2 = last ? nB : cB + (size_t)(t + 2) * kstep;
;             const char* a3 = a2 + kstep; const char* b3 = b2 + kstep;
;             if (last && has_next) S.a_ready(nxt);
;             if constexpr (SP2) {
;             PG8_LDB(B0, 0, 0); PG8_LDB(B1, 0, 1); PG8_SCHED; PG8_LDA(At, 0, 0); PG8_STAGE(PG8_SA(1, 1), a1 + hstep, voffA);
.LBB0_52:
	s_add_i32 s84, 0, 0x10000
	s_add_i32 s85, 0, 0x14000
	ds_read_b128 v[142:145], v200
	ds_read_b128 v[146:149], v200 offset:1024
	ds_read_b128 v[150:153], v200 offset:2048
	ds_read_b128 v[154:157], v200 offset:3072
	ds_read_b128 v[164:167], v200 offset:16384
	ds_read_b128 v[168:171], v200 offset:17408
	ds_read_b128 v[172:175], v200 offset:18432
	ds_read_b128 v[176:179], v200 offset:19456
	s_add_i32 m0, s28, 0xc000
	ds_read_b128 v[180:183], v141
	ds_read_b128 v[184:187], v141 offset:1024
	ds_read_b128 v[188:191], v141 offset:2048
	ds_read_b128 v[192:195], v141 offset:3072
	ds_read_b128 v[196:199], v141 offset:4096
	ds_read_b128 v[222:225], v141 offset:5120
	ds_read_b128 v[226:229], v141 offset:6144
	global_load_lds_dwordx4 v134, s[72:73]
	s_add_i32 m0, s28, 0xe000
	ds_read_b128 v[230:233], v141 offset:7168
	global_load_lds_dwordx4 v136, s[72:73]
	s_add_u32 s4, s72, 0x100
	s_addc_u32 s5, s73, 0
	s_cmpk_eq_i32 s83, 0x54
	s_cselect_b32 s57, s45, s5
	s_cselect_b32 s56, s44, s4
	s_cselect_b32 s53, s55, s82
	s_cselect_b32 s52, s54, s81

; #define PG8_STAGE(bufoff, gbase, voff) do { _Pragma("unroll") for (int _i = 0; _i < 2; ++_i) \
;         __builtin_amdgcn_global_load_lds((const unsigned*)((const char*)(gbase) + (voff)[_i]), (PG8_LAS unsigned*)(lds + (bufoff) + ldsw + _i * 8192), 16, 0, 0); } while (0)
; #define PG8_LDA(dst, b, h) do { _Pragma("unroll") for (int m = 0; m < 4; ++m) _Pragma("unroll") for (int k = 0; k < 2; ++k) dst[m][k] = *(const PG8_LAS bf16x8*)(lds + PG8_SA(b, h) + aoff + m * 2048 + k * 1024); } while (0)
; #define PG8_MMA(ai, bj, At, Bt) do { __builtin_amdgcn_s_setprio(1); _Pragma("unroll") for (int m = 0; m < 4; ++m) _Pragma("unroll") for (int n = 0; n < 2; ++n) _Pragma("unroll") for (int k = 0; k < 2; ++k) \
;         acc[ai][bj][m][n] = __builtin_amdgcn_mfma_f32_16x16x32_bf16(Bt[n][k], At[m][k], acc[ai][bj][m][n], 0, 0, 0); __builtin_amdgcn_s_setprio(0); } while (0)
; #define PG8_WAIT_V(n) asm volatile("s_waitcnt vmcnt(" #n ")" ::: "memory")
; #define PG8_WAIT_L(n) asm volatile("s_waitcnt lgkmcnt(" #n ")" ::: "memory")
; #define PG8_BAR __builtin_amdgcn_s_barrier()
; #define PG8_SCHED __builtin_amdgcn_sched_barrier(0)
; template <class Epi, class Sched, bool ALIGN_EPI = false, bool SP2 = false>
; __device__ __forceinline__ void gemm_phase(PG8_LAS unsigned char* lds, const Gemm g, const Sched& S, const Epi& E) {
;     ...
;             PG8_WAIT_V(8); PG8_WAIT_L(0); PG8_BAR; PG8_MMA(0, 0, At, B0); PG8_MMA(0, 1, At, B1); PG8_BAR; PG8_SCHED;
;             PG8_LDA(At, 0, 1); PG8_STAGE(PG8_SB(0, 0), b2, voffB); PG8_STAGE(PG8_SB(0, 1), b2 + hstep, voffB); PG8_STAGE(PG8_SA(0, 0), a2, voffA);
	s_waitcnt vmcnt(8)
	s_waitcnt lgkmcnt(0)
	s_barrier
	s_waitcnt lgkmcnt(0)
	v_mfma_f32_16x16x32_bf16 v[124:127], v[142:145], v[180:183], v[124:127]
	v_mfma_f32_16x16x32_bf16 v[120:123], v[150:153], v[180:183], v[120:123]
	v_mfma_f32_16x16x32_bf16 v[116:119], v[142:145], v[188:191], v[116:119]
	v_mfma_f32_16x16x32_bf16 v[112:115], v[150:153], v[188:191], v[112:115]
	v_mfma_f32_16x16x32_bf16 v[100:103], v[142:145], v[196:199], v[100:103]
	v_mfma_f32_16x16x32_bf16 v[96:99], v[150:153], v[196:199], v[96:99]
	v_mfma_f32_16x16x32_bf16 v[84:87], v[142:145], v[226:229], v[84:87]
	v_mfma_f32_16x16x32_bf16 v[80:83], v[150:153], v[226:229], v[80:83]
	v_mfma_f32_16x16x32_bf16 v[124:127], v[146:149], v[184:187], v[124:127]
	v_mfma_f32_16x16x32_bf16 v[120:123], v[154:157], v[184:187], v[120:123]
	v_mfma_f32_16x16x32_bf16 v[116:119], v[146:149], v[192:195], v[116:119]
	v_mfma_f32_16x16x32_bf16 v[112:115], v[154:157], v[192:195], v[112:115]
	v_mfma_f32_16x16x32_bf16 v[100:103], v[146:149], v[222:225], v[100:103]
	v_mfma_f32_16x16x32_bf16 v[96:99], v[154:157], v[222:225], v[96:99]
	v_mfma_f32_16x16x32_bf16 v[84:87], v[146:149], v[230:233], v[84:87]
	v_mfma_f32_16x16x32_bf16 v[80:83], v[154:157], v[230:233], v[80:83]
	v_mfma_f32_16x16x32_bf16 v[108:111], v[164:167], v[180:183], v[108:111]
	v_mfma_f32_16x16x32_bf16 v[104:107], v[172:175], v[180:183], v[104:107]
	v_mfma_f32_16x16x32_bf16 v[92:95], v[164:167], v[188:191], v[92:95]
	v_mfma_f32_16x16x32_bf16 v[88:91], v[172:175], v[188:191], v[88:91]
	v_mfma_f32_16x16x32_bf16 v[76:79], v[164:167], v[196:199], v[76:79]
	v_mfma_f32_16x16x32_bf16 v[72:75], v[172:175], v[196:199], v[72:75]
	v_mfma_f32_16x16x32_bf16 v[68:71], v[164:167], v[226:229], v[68:71]
	v_mfma_f32_16x16x32_bf16 v[64:67], v[172:175], v[226:229], v[64:67]
	v_mfma_f32_16x16x32_bf16 v[108:111], v[168:171], v[184:187], v[108:111]
	v_mfma_f32_16x16x32_bf16 v[104:107], v[176:179], v[184:187], v[104:107]
	v_mfma_f32_16x16x32_bf16 v[92:95], v[168:171], v[192:195], v[92:95]
	v_mfma_f32_16x16x32_bf16 v[88:91], v[176:179], v[192:195], v[88:91]
	v_mfma_f32_16x16x32_bf16 v[76:79], v[168:171], v[222:225], v[76:79]
	v_mfma_f32_16x16x32_bf16 v[72:75], v[176:179], v[222:225], v[72:75]
	v_mfma_f32_16x16x32_bf16 v[68:71], v[168:171], v[230:233], v[68:71]
	v_mfma_f32_16x16x32_bf16 v[64:67], v[176:179], v[230:233], v[64:67]
	s_barrier
	s_add_i32 s72, s84, s24
	s_mov_b32 m0, s72
	ds_read_b128 v[180:183], v141 offset:16384
	ds_read_b128 v[184:187], v141 offset:17408
	ds_read_b128 v[188:191], v141 offset:18432
	ds_read_b128 v[192:195], v141 offset:19456
	global_load_lds_dwordx4 v160, s[52:53]
	s_add_i32 m0, s72, 0x2000
	s_add_u32 s72, s52, 0x160000
	s_addc_u32 s73, s53, 0
	s_add_i32 s84, s85, s24
	global_load_lds_dwordx4 v128, s[52:53]
	s_mov_b32 m0, s84
	ds_read_b128 v[196:199], v141 offset:20480
	global_load_lds_dwordx4 v160, s[72:73]
	s_add_i32 m0, s84, 0x2000
	ds_read_b128 v[222:225], v141 offset:21504
	global_load_lds_dwordx4 v128, s[72:73]
	s_mov_b32 m0, s28
	ds_read_b128 v[226:229], v141 offset:22528
	global_load_lds_dwordx4 v132, s[56:57]
	s_mov_b32 m0, s29
	ds_read_b128 v[230:233], v141 offset:23552
	global_load_lds_dwordx4 v130, s[56:57]
	s_add_u32 s98, s56, 0x80
	s_addc_u32 s99, s57, 0


; #define PG8_STAGE(bufoff, gbase, voff) do { _Pragma("unroll") for (int _i = 0; _i < 2; ++_i) \
;         __builtin_amdgcn_global_load_lds((const unsigned*)((const char*)(gbase) + (voff)[_i]), (PG8_LAS unsigned*)(lds + (bufoff) + ldsw + _i * 8192), 16, 0, 0); } while (0)
; #define PG8_LDA(dst, b, h) do { _Pragma("unroll") for (int m = 0; m < 4; ++m) _Pragma("unroll") for (int k = 0; k < 2; ++k) dst[m][k] = *(const PG8_LAS bf16x8*)(lds + PG8_SA(b, h) + aoff + m * 2048 + k * 1024); } while (0)
; #define PG8_LDB(dst, b, h) do { _Pragma("unroll") for (int n = 0; n < 2; ++n) _Pragma("unroll") for (int k = 0; k < 2; ++k) dst[n][k] = *(const PG8_LAS bf16x8*)(lds + PG8_SB(b, h) + boff + n * 2048 + k * 1024); } while (0)
; #define PG8_MMA(ai, bj, At, Bt) do { __builtin_amdgcn_s_setprio(1); _Pragma("unroll") for (int m = 0; m < 4; ++m) _Pragma("unroll") for (int n = 0; n < 2; ++n) _Pragma("unroll") for (int k = 0; k < 2; ++k) \
;         acc[ai][bj][m][n] = __builtin_amdgcn_mfma_f32_16x16x32_bf16(Bt[n][k], At[m][k], acc[ai][bj][m][n], 0, 0, 0); __builtin_amdgcn_s_setprio(0); } while (0)
; #define PG8_WAIT_V(n) asm volatile("s_waitcnt vmcnt(" #n ")" ::: "memory")
; #define PG8_WAIT_L(n) asm volatile("s_waitcnt lgkmcnt(" #n ")" ::: "memory")
; #define PG8_BAR __builtin_amdgcn_s_barrier()
; #define PG8_SCHED __builtin_amdgcn_sched_barrier(0)
; template <class Epi, class Sched, bool ALIGN_EPI = false, bool SP2 = false>
; __device__ __forceinline__ void gemm_phase(PG8_LAS unsigned char* lds, const Gemm g, const Sched& S, const Epi& E) {
;     ...
;             PG8_WAIT_V(8); PG8_WAIT_L(0); PG8_BAR; PG8_MMA(1, 0, At, B0); PG8_MMA(1, 1, At, B1); PG8_BAR; PG8_SCHED;
;             PG8_LDB(B0, 1, 0); PG8_LDB(B1, 1, 1); PG8_SCHED; PG8_LDA(At, 1, 0); PG8_STAGE(PG8_SA(0, 1), a2 + hstep, voffA);
	s_waitcnt vmcnt(8)
	s_waitcnt lgkmcnt(0)
	s_barrier
	s_waitcnt lgkmcnt(0)
	v_mfma_f32_16x16x32_bf16 v[60:63], v[142:145], v[180:183], v[60:63]
	v_mfma_f32_16x16x32_bf16 v[56:59], v[150:153], v[180:183], v[56:59]
	v_mfma_f32_16x16x32_bf16 v[52:55], v[142:145], v[188:191], v[52:55]
	v_mfma_f32_16x16x32_bf16 v[48:51], v[150:153], v[188:191], v[48:51]
	v_mfma_f32_16x16x32_bf16 v[36:39], v[142:145], v[196:199], v[36:39]
	v_mfma_f32_16x16x32_bf16 v[32:35], v[150:153], v[196:199], v[32:35]
	v_mfma_f32_16x16x32_bf16 v[20:23], v[142:145], v[226:229], v[20:23]
	v_mfma_f32_16x16x32_bf16 v[16:19], v[150:153], v[226:229], v[16:19]
	v_mfma_f32_16x16x32_bf16 v[60:63], v[146:149], v[184:187], v[60:63]
	v_mfma_f32_16x16x32_bf16 v[56:59], v[154:157], v[184:187], v[56:59]
	v_mfma_f32_16x16x32_bf16 v[52:55], v[146:149], v[192:195], v[52:55]
	v_mfma_f32_16x16x32_bf16 v[48:51], v[154:157], v[192:195], v[48:51]
	v_mfma_f32_16x16x32_bf16 v[36:39], v[146:149], v[222:225], v[36:39]
	v_mfma_f32_16x16x32_bf16 v[32:35], v[154:157], v[222:225], v[32:35]
	v_mfma_f32_16x16x32_bf16 v[20:23], v[146:149], v[230:233], v[20:23]
	v_mfma_f32_16x16x32_bf16 v[16:19], v[154:157], v[230:233], v[16:19]
	v_mfma_f32_16x16x32_bf16 v[44:47], v[164:167], v[180:183], v[44:47]
	v_mfma_f32_16x16x32_bf16 v[40:43], v[172:175], v[180:183], v[40:43]
	v_mfma_f32_16x16x32_bf16 v[28:31], v[164:167], v[188:191], v[28:31]
	v_mfma_f32_16x16x32_bf16 v[24:27], v[172:175], v[188:191], v[24:27]
	v_mfma_f32_16x16x32_bf16 v[12:15], v[164:167], v[196:199], v[12:15]
	v_mfma_f32_16x16x32_bf16 v[8:11], v[172:175], v[196:199], v[8:11]
	v_mfma_f32_16x16x32_bf16 v[4:7], v[164:167], v[226:229], v[4:7]
	v_mfma_f32_16x16x32_bf16 v[0:3], v[172:175], v[226:229], v[0:3]
	v_mfma_f32_16x16x32_bf16 v[44:47], v[168:171], v[184:187], v[44:47]
	v_mfma_f32_16x16x32_bf16 v[40:43], v[176:179], v[184:187], v[40:43]
	v_mfma_f32_16x16x32_bf16 v[28:31], v[168:171], v[192:195], v[28:31]
	v_mfma_f32_16x16x32_bf16 v[24:27], v[176:179], v[192:195], v[24:27]
	v_mfma_f32_16x16x32_bf16 v[12:15], v[168:171], v[222:225], v[12:15]
	v_mfma_f32_16x16x32_bf16 v[8:11], v[176:179], v[222:225], v[8:11]
	v_mfma_f32_16x16x32_bf16 v[4:7], v[168:171], v[230:233], v[4:7]
	v_mfma_f32_16x16x32_bf16 v[0:3], v[176:179], v[230:233], v[0:3]
	s_barrier
	s_add_i32 s72, 0, 0x18000
	s_add_i32 s73, 0, 0x1c000
	ds_read_b128 v[142:145], v200 offset:32768
	ds_read_b128 v[146:149], v200 offset:33792
	ds_read_b128 v[150:153], v200 offset:34816
	ds_read_b128 v[154:157], v200 offset:35840
	ds_read_b128 v[164:167], v200 offset:49152
	ds_read_b128 v[168:171], v200 offset:50176
	ds_read_b128 v[172:175], v200 offset:51200
	ds_read_b128 v[176:179], v200 offset:52224
	s_add_u32 s56, s56, 0x160000
	s_addc_u32 s57, s57, 0
	s_mov_b32 m0, s59
	ds_read_b128 v[180:183], v141 offset:32768
	ds_read_b128 v[184:187], v141 offset:33792
	ds_read_b128 v[188:191], v141 offset:34816
	ds_read_b128 v[192:195], v141 offset:35840
	ds_read_b128 v[196:199], v141 offset:36864
	ds_read_b128 v[222:225], v141 offset:37888
	ds_read_b128 v[226:229], v141 offset:38912
	global_load_lds_dwordx4 v132, s[56:57]
	s_mov_b32 m0, s63
	ds_read_b128 v[230:233], v141 offset:39936
	global_load_lds_dwordx4 v130, s[56:57]

; #define PG8_STAGE(bufoff, gbase, voff) do { _Pragma("unroll") for (int _i = 0; _i < 2; ++_i) \
;         __builtin_amdgcn_global_load_lds((const unsigned*)((const char*)(gbase) + (voff)[_i]), (PG8_LAS unsigned*)(lds + (bufoff) + ldsw + _i * 8192), 16, 0, 0); } while (0)
; #define PG8_LDA(dst, b, h) do { _Pragma("unroll") for (int m = 0; m < 4; ++m) _Pragma("unroll") for (int k = 0; k < 2; ++k) dst[m][k] = *(const PG8_LAS bf16x8*)(lds + PG8_SA(b, h) + aoff + m * 2048 + k * 1024); } while (0)
; #define PG8_MMA(ai, bj, At, Bt) do { __builtin_amdgcn_s_setprio(1); _Pragma("unroll") for (int m = 0; m < 4; ++m) _Pragma("unroll") for (int n = 0; n < 2; ++n) _Pragma("unroll") for (int k = 0; k < 2; ++k) \
;         acc[ai][bj][m][n] = __builtin_amdgcn_mfma_f32_16x16x32_bf16(Bt[n][k], At[m][k], acc[ai][bj][m][n], 0, 0, 0); __builtin_amdgcn_s_setprio(0); } while (0)
; #define PG8_WAIT_V(n) asm volatile("s_waitcnt vmcnt(" #n ")" ::: "memory")
; #define PG8_WAIT_L(n) asm volatile("s_waitcnt lgkmcnt(" #n ")" ::: "memory")
; #define PG8_BAR __builtin_amdgcn_s_barrier()
; #define PG8_SCHED __builtin_amdgcn_sched_barrier(0)
; template <class Epi, class Sched, bool ALIGN_EPI = false, bool SP2 = false>
; __device__ __forceinline__ void gemm_phase(PG8_LAS unsigned char* lds, const Gemm g, const Sched& S, const Epi& E) {
;     ...
;             PG8_WAIT_V(8); PG8_WAIT_L(0); PG8_BAR; PG8_MMA(0, 0, At, B0); PG8_MMA(0, 1, At, B1); PG8_BAR; PG8_SCHED;
;             PG8_LDA(At, 1, 1); PG8_STAGE(PG8_SB(1, 0), b3, voffB); PG8_STAGE(PG8_SB(1, 1), b3 + hstep, voffB); PG8_STAGE(PG8_SA(1, 0), a3, voffA);
	s_waitcnt vmcnt(8)
	s_waitcnt lgkmcnt(0)
	s_barrier
	s_waitcnt lgkmcnt(0)
	v_mfma_f32_16x16x32_bf16 v[124:127], v[142:145], v[180:183], v[124:127]
	v_mfma_f32_16x16x32_bf16 v[120:123], v[150:153], v[180:183], v[120:123]
	v_mfma_f32_16x16x32_bf16 v[116:119], v[142:145], v[188:191], v[116:119]
	v_mfma_f32_16x16x32_bf16 v[112:115], v[150:153], v[188:191], v[112:115]
	v_mfma_f32_16x16x32_bf16 v[100:103], v[142:145], v[196:199], v[100:103]
	v_mfma_f32_16x16x32_bf16 v[96:99], v[150:153], v[196:199], v[96:99]
	v_mfma_f32_16x16x32_bf16 v[84:87], v[142:145], v[226:229], v[84:87]
	v_mfma_f32_16x16x32_bf16 v[80:83], v[150:153], v[226:229], v[80:83]
	v_mfma_f32_16x16x32_bf16 v[124:127], v[146:149], v[184:187], v[124:127]
	v_mfma_f32_16x16x32_bf16 v[120:123], v[154:157], v[184:187], v[120:123]
	v_mfma_f32_16x16x32_bf16 v[116:119], v[146:149], v[192:195], v[116:119]
	v_mfma_f32_16x16x32_bf16 v[112:115], v[154:157], v[192:195], v[112:115]
	v_mfma_f32_16x16x32_bf16 v[100:103], v[146:149], v[222:225], v[100:103]
	v_mfma_f32_16x16x32_bf16 v[96:99], v[154:157], v[222:225], v[96:99]
	v_mfma_f32_16x16x32_bf16 v[84:87], v[146:149], v[230:233], v[84:87]
	v_mfma_f32_16x16x32_bf16 v[80:83], v[154:157], v[230:233], v[80:83]
	v_mfma_f32_16x16x32_bf16 v[108:111], v[164:167], v[180:183], v[108:111]
	v_mfma_f32_16x16x32_bf16 v[104:107], v[172:175], v[180:183], v[104:107]
	v_mfma_f32_16x16x32_bf16 v[92:95], v[164:167], v[188:191], v[92:95]
	v_mfma_f32_16x16x32_bf16 v[88:91], v[172:175], v[188:191], v[88:91]
	v_mfma_f32_16x16x32_bf16 v[76:79], v[164:167], v[196:199], v[76:79]
	v_mfma_f32_16x16x32_bf16 v[72:75], v[172:175], v[196:199], v[72:75]
	v_mfma_f32_16x16x32_bf16 v[68:71], v[164:167], v[226:229], v[68:71]
	v_mfma_f32_16x16x32_bf16 v[64:67], v[172:175], v[226:229], v[64:67]
	v_mfma_f32_16x16x32_bf16 v[108:111], v[168:171], v[184:187], v[108:111]
	v_mfma_f32_16x16x32_bf16 v[104:107], v[176:179], v[184:187], v[104:107]
	v_mfma_f32_16x16x32_bf16 v[92:95], v[168:171], v[192:195], v[92:95]
	v_mfma_f32_16x16x32_bf16 v[88:91], v[176:179], v[192:195], v[88:91]
	v_mfma_f32_16x16x32_bf16 v[76:79], v[168:171], v[222:225], v[76:79]
	v_mfma_f32_16x16x32_bf16 v[72:75], v[176:179], v[222:225], v[72:75]
	v_mfma_f32_16x16x32_bf16 v[68:71], v[168:171], v[230:233], v[68:71]
	v_mfma_f32_16x16x32_bf16 v[64:67], v[176:179], v[230:233], v[64:67]
	s_barrier
	s_add_i32 s56, s72, s24
	s_mov_b32 m0, s56
	ds_read_b128 v[180:183], v141 offset:49152
	ds_read_b128 v[184:187], v141 offset:50176
	ds_read_b128 v[188:191], v141 offset:51200
	ds_read_b128 v[192:195], v141 offset:52224
	s_add_u32 s52, s52, 0x80
	s_addc_u32 s53, s53, 0
	global_load_lds_dwordx4 v160, s[52:53]
	s_add_i32 m0, s56, 0x2000
	s_add_i32 s56, s73, s24
	global_load_lds_dwordx4 v128, s[52:53]
	s_add_u32 s52, s52, 0x160000
	s_addc_u32 s53, s53, 0
	s_mov_b32 m0, s56
	ds_read_b128 v[196:199], v141 offset:53248
	global_load_lds_dwordx4 v160, s[52:53]
	s_add_i32 m0, s56, 0x2000
	ds_read_b128 v[222:225], v141 offset:54272
	global_load_lds_dwordx4 v128, s[52:53]
	s_mov_b32 m0, s74
	ds_read_b128 v[226:229], v141 offset:55296
	global_load_lds_dwordx4 v132, s[98:99]
	s_mov_b32 m0, s75
	ds_read_b128 v[230:233], v141 offset:56320
	global_load_lds_dwordx4 v130, s[98:99]


; #define PG8_MMA(ai, bj, At, Bt) do { __builtin_amdgcn_s_setprio(1); _Pragma("unroll") for (int m = 0; m < 4; ++m) _Pragma("unroll") for (int n = 0; n < 2; ++n) _Pragma("unroll") for (int k = 0; k < 2; ++k) \
;         acc[ai][bj][m][n] = __builtin_amdgcn_mfma_f32_16x16x32_bf16(Bt[n][k], At[m][k], acc[ai][bj][m][n], 0, 0, 0); __builtin_amdgcn_s_setprio(0); } while (0)
; #define PG8_WAIT_V(n) asm volatile("s_waitcnt vmcnt(" #n ")" ::: "memory")
; #define PG8_WAIT_L(n) asm volatile("s_waitcnt lgkmcnt(" #n ")" ::: "memory")
; #define PG8_BAR __builtin_amdgcn_s_barrier()
; #define PG8_SCHED __builtin_amdgcn_sched_barrier(0)
; template <class Epi, class Sched, bool ALIGN_EPI = false, bool SP2 = false>
; __device__ __forceinline__ void gemm_phase(PG8_LAS unsigned char* lds, const Gemm g, const Sched& S, const Epi& E) {
;     ...
;         for (int t = 0; t < nt; t += 2) {
;     ...
;             PG8_WAIT_V(8); PG8_WAIT_L(0); PG8_BAR; PG8_MMA(1, 0, At, B0); PG8_MMA(1, 1, At, B1); PG8_BAR; PG8_SCHED;
	s_waitcnt vmcnt(8)
	s_waitcnt lgkmcnt(0)
	s_barrier
	s_waitcnt lgkmcnt(0)
	v_mfma_f32_16x16x32_bf16 v[60:63], v[142:145], v[180:183], v[60:63]
	v_mfma_f32_16x16x32_bf16 v[56:59], v[150:153], v[180:183], v[56:59]
	v_mfma_f32_16x16x32_bf16 v[52:55], v[142:145], v[188:191], v[52:55]
	v_mfma_f32_16x16x32_bf16 v[48:51], v[150:153], v[188:191], v[48:51]
	v_mfma_f32_16x16x32_bf16 v[36:39], v[142:145], v[196:199], v[36:39]
	v_mfma_f32_16x16x32_bf16 v[32:35], v[150:153], v[196:199], v[32:35]
	v_mfma_f32_16x16x32_bf16 v[20:23], v[142:145], v[226:229], v[20:23]
	v_mfma_f32_16x16x32_bf16 v[16:19], v[150:153], v[226:229], v[16:19]
	v_mfma_f32_16x16x32_bf16 v[60:63], v[146:149], v[184:187], v[60:63]
	v_mfma_f32_16x16x32_bf16 v[56:59], v[154:157], v[184:187], v[56:59]
	v_mfma_f32_16x16x32_bf16 v[52:55], v[146:149], v[192:195], v[52:55]
	v_mfma_f32_16x16x32_bf16 v[48:51], v[154:157], v[192:195], v[48:51]
	v_mfma_f32_16x16x32_bf16 v[36:39], v[146:149], v[222:225], v[36:39]
	v_mfma_f32_16x16x32_bf16 v[32:35], v[154:157], v[222:225], v[32:35]
	v_mfma_f32_16x16x32_bf16 v[20:23], v[146:149], v[230:233], v[20:23]
	v_mfma_f32_16x16x32_bf16 v[16:19], v[154:157], v[230:233], v[16:19]
	v_mfma_f32_16x16x32_bf16 v[44:47], v[164:167], v[180:183], v[44:47]
	v_mfma_f32_16x16x32_bf16 v[40:43], v[172:175], v[180:183], v[40:43]
	v_mfma_f32_16x16x32_bf16 v[28:31], v[164:167], v[188:191], v[28:31]
	v_mfma_f32_16x16x32_bf16 v[24:27], v[172:175], v[188:191], v[24:27]
	v_mfma_f32_16x16x32_bf16 v[12:15], v[164:167], v[196:199], v[12:15]
	v_mfma_f32_16x16x32_bf16 v[8:11], v[172:175], v[196:199], v[8:11]
	v_mfma_f32_16x16x32_bf16 v[4:7], v[164:167], v[226:229], v[4:7]
	v_mfma_f32_16x16x32_bf16 v[0:3], v[172:175], v[226:229], v[0:3]
	v_mfma_f32_16x16x32_bf16 v[44:47], v[168:171], v[184:187], v[44:47]
	v_mfma_f32_16x16x32_bf16 v[40:43], v[176:179], v[184:187], v[40:43]
	v_mfma_f32_16x16x32_bf16 v[28:31], v[168:171], v[192:195], v[28:31]
	v_mfma_f32_16x16x32_bf16 v[24:27], v[176:179], v[192:195], v[24:27]
	v_mfma_f32_16x16x32_bf16 v[12:15], v[168:171], v[222:225], v[12:15]
	v_mfma_f32_16x16x32_bf16 v[8:11], v[176:179], v[222:225], v[8:11]
	v_mfma_f32_16x16x32_bf16 v[4:7], v[168:171], v[230:233], v[4:7]
	v_mfma_f32_16x16x32_bf16 v[0:3], v[176:179], v[230:233], v[0:3]
	s_barrier
	s_add_i32 s83, s83, 2
	s_add_u32 s81, s81, 0x100
	s_addc_u32 s82, s82, 0
	s_cmpk_gt_u32 s83, 0x55
	s_mov_b64 s[72:73], s[4:5]
	s_cbranch_scc0 .LBB0_52
	s_and_b64 vcc, exec, s[42:43]
	s_cbranch_vccz .LBB0_55
	s_barrier

; #define PG8_STAGE(bufoff, gbase, voff) do { _Pragma("unroll") for (int _i = 0; _i < 2; ++_i) \
;         __builtin_amdgcn_global_load_lds((const unsigned*)((const char*)(gbase) + (voff)[_i]), (PG8_LAS unsigned*)(lds + (bufoff) + ldsw + _i * 8192), 16, 0, 0); } while (0)
; #define PG8_LDA(dst, b, h) do { _Pragma("unroll") for (int m = 0; m < 4; ++m) _Pragma("unroll") for (int k = 0; k < 2; ++k) dst[m][k] = *(const PG8_LAS bf16x8*)(lds + PG8_SA(b, h) + aoff + m * 2048 + k * 1024); } while (0)
; #define PG8_LDB(dst, b, h) do { _Pragma("unroll") for (int n = 0; n < 2; ++n) _Pragma("unroll") for (int k = 0; k < 2; ++k) dst[n][k] = *(const PG8_LAS bf16x8*)(lds + PG8_SB(b, h) + boff + n * 2048 + k * 1024); } while (0)
; #define PG8_SCHED __builtin_amdgcn_sched_barrier(0)
; template <class Epi, class Sched, bool ALIGN_EPI = false, bool SP2 = false>
; __device__ __forceinline__ void gemm_phase(PG8_LAS unsigned char* lds, const Gemm g, const Sched& S, const Epi& E) {
;     ...
;             const char* a1 = cA + (size_t)(t + 1) * kstep;
;             const char* a2 = last ? nA : cA + (size_t)(t + 2) * kstep; const char* b2 = last ? nB : cB + (size_t)(t + 2) * kstep;
;             const char* a3 = a2 + kstep; const char* b3 = b2 + kstep;
;             if (last && has_next) S.a_ready(nxt);
;             if constexpr (SP2) {
;             PG8_LDB(B0, 0, 0); PG8_LDB(B1, 0, 1); PG8_SCHED; PG8_LDA(At, 0, 0); PG8_STAGE(PG8_SA(1, 1), a1 + hstep, voffA);
.LBB0_86:
	s_add_i32 s88, 0, 0x10000
	s_add_i32 s90, 0, 0x14000
	ds_read_b128 v[140:143], v200
	ds_read_b128 v[150:153], v200 offset:1024
	ds_read_b128 v[154:157], v200 offset:2048
	ds_read_b128 v[164:167], v200 offset:3072
	ds_read_b128 v[168:171], v200 offset:16384
	ds_read_b128 v[172:175], v200 offset:17408
	ds_read_b128 v[176:179], v200 offset:18432
	ds_read_b128 v[180:183], v200 offset:19456
	s_add_i32 m0, s63, 0xc000
	ds_read_b128 v[184:187], v149
	ds_read_b128 v[188:191], v149 offset:1024
	ds_read_b128 v[192:195], v149 offset:2048
	ds_read_b128 v[196:199], v149 offset:3072
	ds_read_b128 v[222:225], v149 offset:4096
	ds_read_b128 v[226:229], v149 offset:5120
	ds_read_b128 v[230:233], v149 offset:6144
	global_load_lds_dwordx4 v136, s[82:83]
	s_add_i32 m0, s63, 0xe000
	ds_read_b128 v[234:237], v149 offset:7168
	global_load_lds_dwordx4 v138, s[82:83]
	s_add_u32 s4, s82, 0xfffc0080
	s_addc_u32 s5, s83, -1
	s_cmp_eq_u32 s87, 12
	s_cselect_b32 s53, s7, s5
	s_cselect_b32 s52, s15, s4
	s_cselect_b32 s5, s24, s43
	s_cselect_b32 s4, s28, s29

; #define PG8_STAGE(bufoff, gbase, voff) do { _Pragma("unroll") for (int _i = 0; _i < 2; ++_i) \
;         __builtin_amdgcn_global_load_lds((const unsigned*)((const char*)(gbase) + (voff)[_i]), (PG8_LAS unsigned*)(lds + (bufoff) + ldsw + _i * 8192), 16, 0, 0); } while (0)
; #define PG8_LDA(dst, b, h) do { _Pragma("unroll") for (int m = 0; m < 4; ++m) _Pragma("unroll") for (int k = 0; k < 2; ++k) dst[m][k] = *(const PG8_LAS bf16x8*)(lds + PG8_SA(b, h) + aoff + m * 2048 + k * 1024); } while (0)
; #define PG8_MMA(ai, bj, At, Bt) do { __builtin_amdgcn_s_setprio(1); _Pragma("unroll") for (int m = 0; m < 4; ++m) _Pragma("unroll") for (int n = 0; n < 2; ++n) _Pragma("unroll") for (int k = 0; k < 2; ++k) \
;         acc[ai][bj][m][n] = __builtin_amdgcn_mfma_f32_16x16x32_bf16(Bt[n][k], At[m][k], acc[ai][bj][m][n], 0, 0, 0); __builtin_amdgcn_s_setprio(0); } while (0)
; #define PG8_WAIT_V(n) asm volatile("s_waitcnt vmcnt(" #n ")" ::: "memory")
; #define PG8_WAIT_L(n) asm volatile("s_waitcnt lgkmcnt(" #n ")" ::: "memory")
; #define PG8_BAR __builtin_amdgcn_s_barrier()
; #define PG8_SCHED __builtin_amdgcn_sched_barrier(0)
; template <class Epi, class Sched, bool ALIGN_EPI = false, bool SP2 = false>
; __device__ __forceinline__ void gemm_phase(PG8_LAS unsigned char* lds, const Gemm g, const Sched& S, const Epi& E) {
;     ...
;             PG8_WAIT_V(8); PG8_WAIT_L(0); PG8_BAR; PG8_MMA(0, 0, At, B0); PG8_MMA(0, 1, At, B1); PG8_BAR; PG8_SCHED;
;             PG8_LDA(At, 0, 1); PG8_STAGE(PG8_SB(0, 0), b2, voffB); PG8_STAGE(PG8_SB(0, 1), b2 + hstep, voffB); PG8_STAGE(PG8_SA(0, 0), a2, voffA);
	s_waitcnt vmcnt(8)
	s_waitcnt lgkmcnt(0)
	s_barrier
	s_waitcnt lgkmcnt(0)
	v_mfma_f32_16x16x32_bf16 v[124:127], v[140:143], v[184:187], v[124:127]
	v_mfma_f32_16x16x32_bf16 v[120:123], v[154:157], v[184:187], v[120:123]
	v_mfma_f32_16x16x32_bf16 v[108:111], v[140:143], v[192:195], v[108:111]
	v_mfma_f32_16x16x32_bf16 v[104:107], v[154:157], v[192:195], v[104:107]
	v_mfma_f32_16x16x32_bf16 v[92:95], v[140:143], v[222:225], v[92:95]
	v_mfma_f32_16x16x32_bf16 v[88:91], v[154:157], v[222:225], v[88:91]
	v_mfma_f32_16x16x32_bf16 v[76:79], v[140:143], v[230:233], v[76:79]
	v_mfma_f32_16x16x32_bf16 v[72:75], v[154:157], v[230:233], v[72:75]
	v_mfma_f32_16x16x32_bf16 v[124:127], v[150:153], v[188:191], v[124:127]
	v_mfma_f32_16x16x32_bf16 v[120:123], v[164:167], v[188:191], v[120:123]
	v_mfma_f32_16x16x32_bf16 v[108:111], v[150:153], v[196:199], v[108:111]
	v_mfma_f32_16x16x32_bf16 v[104:107], v[164:167], v[196:199], v[104:107]
	v_mfma_f32_16x16x32_bf16 v[92:95], v[150:153], v[226:229], v[92:95]
	v_mfma_f32_16x16x32_bf16 v[88:91], v[164:167], v[226:229], v[88:91]
	v_mfma_f32_16x16x32_bf16 v[76:79], v[150:153], v[234:237], v[76:79]
	v_mfma_f32_16x16x32_bf16 v[72:75], v[164:167], v[234:237], v[72:75]
	v_mfma_f32_16x16x32_bf16 v[116:119], v[168:171], v[184:187], v[116:119]
	v_mfma_f32_16x16x32_bf16 v[112:115], v[176:179], v[184:187], v[112:115]
	v_mfma_f32_16x16x32_bf16 v[100:103], v[168:171], v[192:195], v[100:103]
	v_mfma_f32_16x16x32_bf16 v[96:99], v[176:179], v[192:195], v[96:99]
	v_mfma_f32_16x16x32_bf16 v[84:87], v[168:171], v[222:225], v[84:87]
	v_mfma_f32_16x16x32_bf16 v[80:83], v[176:179], v[222:225], v[80:83]
	v_mfma_f32_16x16x32_bf16 v[68:71], v[168:171], v[230:233], v[68:71]
	v_mfma_f32_16x16x32_bf16 v[64:67], v[176:179], v[230:233], v[64:67]
	v_mfma_f32_16x16x32_bf16 v[116:119], v[172:175], v[188:191], v[116:119]
	v_mfma_f32_16x16x32_bf16 v[112:115], v[180:183], v[188:191], v[112:115]
	v_mfma_f32_16x16x32_bf16 v[100:103], v[172:175], v[196:199], v[100:103]
	v_mfma_f32_16x16x32_bf16 v[96:99], v[180:183], v[196:199], v[96:99]
	v_mfma_f32_16x16x32_bf16 v[84:87], v[172:175], v[226:229], v[84:87]
	v_mfma_f32_16x16x32_bf16 v[80:83], v[180:183], v[226:229], v[80:83]
	v_mfma_f32_16x16x32_bf16 v[68:71], v[172:175], v[234:237], v[68:71]
	v_mfma_f32_16x16x32_bf16 v[64:67], v[180:183], v[234:237], v[64:67]
	s_barrier
	s_add_i32 s88, s88, s59
	s_mov_b32 m0, s88
	ds_read_b128 v[184:187], v149 offset:16384
	ds_read_b128 v[188:191], v149 offset:17408
	ds_read_b128 v[192:195], v149 offset:18432
	ds_read_b128 v[196:199], v149 offset:19456
	global_load_lds_dwordx4 v130, s[4:5]
	s_add_i32 m0, s88, 0x2000
	s_add_u32 s88, s4, 0x40000
	s_addc_u32 s89, s5, 0
	s_add_i32 s90, s90, s59
	global_load_lds_dwordx4 v134, s[4:5]
	s_mov_b32 m0, s90
	ds_read_b128 v[222:225], v149 offset:20480
	global_load_lds_dwordx4 v130, s[88:89]
	s_add_i32 m0, s90, 0x2000
	ds_read_b128 v[226:229], v149 offset:21504
	global_load_lds_dwordx4 v134, s[88:89]
	s_mov_b32 m0, s63
	ds_read_b128 v[230:233], v149 offset:22528
	global_load_lds_dwordx4 v128, s[52:53]
	s_mov_b32 m0, s74
	ds_read_b128 v[234:237], v149 offset:23552
	global_load_lds_dwordx4 v132, s[52:53]
	s_add_u32 s98, s52, 0x80
	s_addc_u32 s99, s53, 0


; #define PG8_STAGE(bufoff, gbase, voff) do { _Pragma("unroll") for (int _i = 0; _i < 2; ++_i) \
;         __builtin_amdgcn_global_load_lds((const unsigned*)((const char*)(gbase) + (voff)[_i]), (PG8_LAS unsigned*)(lds + (bufoff) + ldsw + _i * 8192), 16, 0, 0); } while (0)
; #define PG8_LDA(dst, b, h) do { _Pragma("unroll") for (int m = 0; m < 4; ++m) _Pragma("unroll") for (int k = 0; k < 2; ++k) dst[m][k] = *(const PG8_LAS bf16x8*)(lds + PG8_SA(b, h) + aoff + m * 2048 + k * 1024); } while (0)
; #define PG8_LDB(dst, b, h) do { _Pragma("unroll") for (int n = 0; n < 2; ++n) _Pragma("unroll") for (int k = 0; k < 2; ++k) dst[n][k] = *(const PG8_LAS bf16x8*)(lds + PG8_SB(b, h) + boff + n * 2048 + k * 1024); } while (0)
; #define PG8_MMA(ai, bj, At, Bt) do { __builtin_amdgcn_s_setprio(1); _Pragma("unroll") for (int m = 0; m < 4; ++m) _Pragma("unroll") for (int n = 0; n < 2; ++n) _Pragma("unroll") for (int k = 0; k < 2; ++k) \
;         acc[ai][bj][m][n] = __builtin_amdgcn_mfma_f32_16x16x32_bf16(Bt[n][k], At[m][k], acc[ai][bj][m][n], 0, 0, 0); __builtin_amdgcn_s_setprio(0); } while (0)
; #define PG8_WAIT_V(n) asm volatile("s_waitcnt vmcnt(" #n ")" ::: "memory")
; #define PG8_WAIT_L(n) asm volatile("s_waitcnt lgkmcnt(" #n ")" ::: "memory")
; #define PG8_BAR __builtin_amdgcn_s_barrier()
; #define PG8_SCHED __builtin_amdgcn_sched_barrier(0)
; template <class Epi, class Sched, bool ALIGN_EPI = false, bool SP2 = false>
; __device__ __forceinline__ void gemm_phase(PG8_LAS unsigned char* lds, const Gemm g, const Sched& S, const Epi& E) {
;     ...
;             PG8_WAIT_V(8); PG8_WAIT_L(0); PG8_BAR; PG8_MMA(1, 0, At, B0); PG8_MMA(1, 1, At, B1); PG8_BAR; PG8_SCHED;
;             PG8_LDB(B0, 1, 0); PG8_LDB(B1, 1, 1); PG8_SCHED; PG8_LDA(At, 1, 0); PG8_STAGE(PG8_SA(0, 1), a2 + hstep, voffA);
	s_waitcnt vmcnt(8)
	s_waitcnt lgkmcnt(0)
	s_barrier
	s_waitcnt lgkmcnt(0)
	v_mfma_f32_16x16x32_bf16 v[60:63], v[140:143], v[184:187], v[60:63]
	v_mfma_f32_16x16x32_bf16 v[56:59], v[154:157], v[184:187], v[56:59]
	v_mfma_f32_16x16x32_bf16 v[44:47], v[140:143], v[192:195], v[44:47]
	v_mfma_f32_16x16x32_bf16 v[40:43], v[154:157], v[192:195], v[40:43]
	v_mfma_f32_16x16x32_bf16 v[28:31], v[140:143], v[222:225], v[28:31]
	v_mfma_f32_16x16x32_bf16 v[24:27], v[154:157], v[222:225], v[24:27]
	v_mfma_f32_16x16x32_bf16 v[12:15], v[140:143], v[230:233], v[12:15]
	v_mfma_f32_16x16x32_bf16 v[8:11], v[154:157], v[230:233], v[8:11]
	v_mfma_f32_16x16x32_bf16 v[60:63], v[150:153], v[188:191], v[60:63]
	v_mfma_f32_16x16x32_bf16 v[56:59], v[164:167], v[188:191], v[56:59]
	v_mfma_f32_16x16x32_bf16 v[44:47], v[150:153], v[196:199], v[44:47]
	v_mfma_f32_16x16x32_bf16 v[40:43], v[164:167], v[196:199], v[40:43]
	v_mfma_f32_16x16x32_bf16 v[28:31], v[150:153], v[226:229], v[28:31]
	v_mfma_f32_16x16x32_bf16 v[24:27], v[164:167], v[226:229], v[24:27]
	v_mfma_f32_16x16x32_bf16 v[12:15], v[150:153], v[234:237], v[12:15]
	v_mfma_f32_16x16x32_bf16 v[8:11], v[164:167], v[234:237], v[8:11]
	v_mfma_f32_16x16x32_bf16 v[52:55], v[168:171], v[184:187], v[52:55]
	v_mfma_f32_16x16x32_bf16 v[48:51], v[176:179], v[184:187], v[48:51]
	v_mfma_f32_16x16x32_bf16 v[36:39], v[168:171], v[192:195], v[36:39]
	v_mfma_f32_16x16x32_bf16 v[32:35], v[176:179], v[192:195], v[32:35]
	v_mfma_f32_16x16x32_bf16 v[20:23], v[168:171], v[222:225], v[20:23]
	v_mfma_f32_16x16x32_bf16 v[16:19], v[176:179], v[222:225], v[16:19]
	v_mfma_f32_16x16x32_bf16 v[4:7], v[168:171], v[230:233], v[4:7]
	v_mfma_f32_16x16x32_bf16 v[0:3], v[176:179], v[230:233], v[0:3]
	v_mfma_f32_16x16x32_bf16 v[52:55], v[172:175], v[188:191], v[52:55]
	v_mfma_f32_16x16x32_bf16 v[48:51], v[180:183], v[188:191], v[48:51]
	v_mfma_f32_16x16x32_bf16 v[36:39], v[172:175], v[196:199], v[36:39]
	v_mfma_f32_16x16x32_bf16 v[32:35], v[180:183], v[196:199], v[32:35]
	v_mfma_f32_16x16x32_bf16 v[20:23], v[172:175], v[226:229], v[20:23]
	v_mfma_f32_16x16x32_bf16 v[16:19], v[180:183], v[226:229], v[16:19]
	v_mfma_f32_16x16x32_bf16 v[4:7], v[172:175], v[234:237], v[4:7]
	v_mfma_f32_16x16x32_bf16 v[0:3], v[180:183], v[234:237], v[0:3]
	s_barrier
	s_add_i32 s88, 0, 0x18000
	s_add_i32 s89, 0, 0x1c000
	ds_read_b128 v[140:143], v200 offset:32768
	ds_read_b128 v[150:153], v200 offset:33792
	ds_read_b128 v[154:157], v200 offset:34816
	ds_read_b128 v[164:167], v200 offset:35840
	ds_read_b128 v[168:171], v200 offset:49152
	ds_read_b128 v[172:175], v200 offset:50176
	ds_read_b128 v[176:179], v200 offset:51200
	ds_read_b128 v[180:183], v200 offset:52224
	s_add_u32 s52, s52, 0x40000
	s_addc_u32 s53, s53, 0
	s_mov_b32 m0, s75
	ds_read_b128 v[184:187], v149 offset:32768
	ds_read_b128 v[188:191], v149 offset:33792
	ds_read_b128 v[192:195], v149 offset:34816
	ds_read_b128 v[196:199], v149 offset:35840
	ds_read_b128 v[222:225], v149 offset:36864
	ds_read_b128 v[226:229], v149 offset:37888
	ds_read_b128 v[230:233], v149 offset:38912
	global_load_lds_dwordx4 v128, s[52:53]
	s_mov_b32 m0, s81
	ds_read_b128 v[234:237], v149 offset:39936
	global_load_lds_dwordx4 v132, s[52:53]

; #define PG8_STAGE(bufoff, gbase, voff) do { _Pragma("unroll") for (int _i = 0; _i < 2; ++_i) \
;         __builtin_amdgcn_global_load_lds((const unsigned*)((const char*)(gbase) + (voff)[_i]), (PG8_LAS unsigned*)(lds + (bufoff) + ldsw + _i * 8192), 16, 0, 0); } while (0)
; #define PG8_LDA(dst, b, h) do { _Pragma("unroll") for (int m = 0; m < 4; ++m) _Pragma("unroll") for (int k = 0; k < 2; ++k) dst[m][k] = *(const PG8_LAS bf16x8*)(lds + PG8_SA(b, h) + aoff + m * 2048 + k * 1024); } while (0)
; #define PG8_MMA(ai, bj, At, Bt) do { __builtin_amdgcn_s_setprio(1); _Pragma("unroll") for (int m = 0; m < 4; ++m) _Pragma("unroll") for (int n = 0; n < 2; ++n) _Pragma("unroll") for (int k = 0; k < 2; ++k) \
;         acc[ai][bj][m][n] = __builtin_amdgcn_mfma_f32_16x16x32_bf16(Bt[n][k], At[m][k], acc[ai][bj][m][n], 0, 0, 0); __builtin_amdgcn_s_setprio(0); } while (0)
; #define PG8_WAIT_V(n) asm volatile("s_waitcnt vmcnt(" #n ")" ::: "memory")
; #define PG8_WAIT_L(n) asm volatile("s_waitcnt lgkmcnt(" #n ")" ::: "memory")
; #define PG8_BAR __builtin_amdgcn_s_barrier()
; #define PG8_SCHED __builtin_amdgcn_sched_barrier(0)
; template <class Epi, class Sched, bool ALIGN_EPI = false, bool SP2 = false>
; __device__ __forceinline__ void gemm_phase(PG8_LAS unsigned char* lds, const Gemm g, const Sched& S, const Epi& E) {
;     ...
;             PG8_WAIT_V(8); PG8_WAIT_L(0); PG8_BAR; PG8_MMA(0, 0, At, B0); PG8_MMA(0, 1, At, B1); PG8_BAR; PG8_SCHED;
;             PG8_LDA(At, 1, 1); PG8_STAGE(PG8_SB(1, 0), b3, voffB); PG8_STAGE(PG8_SB(1, 1), b3 + hstep, voffB); PG8_STAGE(PG8_SA(1, 0), a3, voffA);
	s_waitcnt vmcnt(8)
	s_waitcnt lgkmcnt(0)
	s_barrier
	s_waitcnt lgkmcnt(0)
	v_mfma_f32_16x16x32_bf16 v[124:127], v[140:143], v[184:187], v[124:127]
	v_mfma_f32_16x16x32_bf16 v[120:123], v[154:157], v[184:187], v[120:123]
	v_mfma_f32_16x16x32_bf16 v[108:111], v[140:143], v[192:195], v[108:111]
	v_mfma_f32_16x16x32_bf16 v[104:107], v[154:157], v[192:195], v[104:107]
	v_mfma_f32_16x16x32_bf16 v[92:95], v[140:143], v[222:225], v[92:95]
	v_mfma_f32_16x16x32_bf16 v[88:91], v[154:157], v[222:225], v[88:91]
	v_mfma_f32_16x16x32_bf16 v[76:79], v[140:143], v[230:233], v[76:79]
	v_mfma_f32_16x16x32_bf16 v[72:75], v[154:157], v[230:233], v[72:75]
	v_mfma_f32_16x16x32_bf16 v[124:127], v[150:153], v[188:191], v[124:127]
	v_mfma_f32_16x16x32_bf16 v[120:123], v[164:167], v[188:191], v[120:123]
	v_mfma_f32_16x16x32_bf16 v[108:111], v[150:153], v[196:199], v[108:111]
	v_mfma_f32_16x16x32_bf16 v[104:107], v[164:167], v[196:199], v[104:107]
	v_mfma_f32_16x16x32_bf16 v[92:95], v[150:153], v[226:229], v[92:95]
	v_mfma_f32_16x16x32_bf16 v[88:91], v[164:167], v[226:229], v[88:91]
	v_mfma_f32_16x16x32_bf16 v[76:79], v[150:153], v[234:237], v[76:79]
	v_mfma_f32_16x16x32_bf16 v[72:75], v[164:167], v[234:237], v[72:75]
	v_mfma_f32_16x16x32_bf16 v[116:119], v[168:171], v[184:187], v[116:119]
	v_mfma_f32_16x16x32_bf16 v[112:115], v[176:179], v[184:187], v[112:115]
	v_mfma_f32_16x16x32_bf16 v[100:103], v[168:171], v[192:195], v[100:103]
	v_mfma_f32_16x16x32_bf16 v[96:99], v[176:179], v[192:195], v[96:99]
	v_mfma_f32_16x16x32_bf16 v[84:87], v[168:171], v[222:225], v[84:87]
	v_mfma_f32_16x16x32_bf16 v[80:83], v[176:179], v[222:225], v[80:83]
	v_mfma_f32_16x16x32_bf16 v[68:71], v[168:171], v[230:233], v[68:71]
	v_mfma_f32_16x16x32_bf16 v[64:67], v[176:179], v[230:233], v[64:67]
	v_mfma_f32_16x16x32_bf16 v[116:119], v[172:175], v[188:191], v[116:119]
	v_mfma_f32_16x16x32_bf16 v[112:115], v[180:183], v[188:191], v[112:115]
	v_mfma_f32_16x16x32_bf16 v[100:103], v[172:175], v[196:199], v[100:103]
	v_mfma_f32_16x16x32_bf16 v[96:99], v[180:183], v[196:199], v[96:99]
	v_mfma_f32_16x16x32_bf16 v[84:87], v[172:175], v[226:229], v[84:87]
	v_mfma_f32_16x16x32_bf16 v[80:83], v[180:183], v[226:229], v[80:83]
	v_mfma_f32_16x16x32_bf16 v[68:71], v[172:175], v[234:237], v[68:71]
	v_mfma_f32_16x16x32_bf16 v[64:67], v[180:183], v[234:237], v[64:67]
	s_barrier
	s_add_i32 s52, s88, s59
	s_mov_b32 m0, s52
	ds_read_b128 v[184:187], v149 offset:49152
	ds_read_b128 v[188:191], v149 offset:50176
	ds_read_b128 v[192:195], v149 offset:51200
	ds_read_b128 v[196:199], v149 offset:52224
	s_add_u32 s4, s4, 0x80
	s_addc_u32 s5, s5, 0
	global_load_lds_dwordx4 v130, s[4:5]
	s_add_i32 m0, s52, 0x2000
	s_add_i32 s52, s89, s59
	global_load_lds_dwordx4 v134, s[4:5]
	s_add_u32 s4, s4, 0x40000
	s_addc_u32 s5, s5, 0
	s_mov_b32 m0, s52
	ds_read_b128 v[222:225], v149 offset:53248
	global_load_lds_dwordx4 v130, s[4:5]
	s_add_i32 m0, s52, 0x2000
	ds_read_b128 v[226:229], v149 offset:54272
	global_load_lds_dwordx4 v134, s[4:5]
	s_mov_b32 m0, s84
	ds_read_b128 v[230:233], v149 offset:55296
	global_load_lds_dwordx4 v128, s[98:99]
	s_mov_b32 m0, s85
	ds_read_b128 v[234:237], v149 offset:56320
	global_load_lds_dwordx4 v132, s[98:99]


; #define PG8_MMA(ai, bj, At, Bt) do { __builtin_amdgcn_s_setprio(1); _Pragma("unroll") for (int m = 0; m < 4; ++m) _Pragma("unroll") for (int n = 0; n < 2; ++n) _Pragma("unroll") for (int k = 0; k < 2; ++k) \
;         acc[ai][bj][m][n] = __builtin_amdgcn_mfma_f32_16x16x32_bf16(Bt[n][k], At[m][k], acc[ai][bj][m][n], 0, 0, 0); __builtin_amdgcn_s_setprio(0); } while (0)
; #define PG8_WAIT_V(n) asm volatile("s_waitcnt vmcnt(" #n ")" ::: "memory")
; #define PG8_WAIT_L(n) asm volatile("s_waitcnt lgkmcnt(" #n ")" ::: "memory")
; #define PG8_BAR __builtin_amdgcn_s_barrier()
; #define PG8_SCHED __builtin_amdgcn_sched_barrier(0)
; template <class Epi, class Sched, bool ALIGN_EPI = false, bool SP2 = false>
; __device__ __forceinline__ void gemm_phase(PG8_LAS unsigned char* lds, const Gemm g, const Sched& S, const Epi& E) {
;     ...
;         for (int t = 0; t < nt; t += 2) {
;     ...
;             PG8_WAIT_V(8); PG8_WAIT_L(0); PG8_BAR; PG8_MMA(1, 0, At, B0); PG8_MMA(1, 1, At, B1); PG8_BAR; PG8_SCHED;
	s_waitcnt vmcnt(8)
	s_waitcnt lgkmcnt(0)
	s_barrier
	s_waitcnt lgkmcnt(0)
	v_mfma_f32_16x16x32_bf16 v[60:63], v[140:143], v[184:187], v[60:63]
	v_mfma_f32_16x16x32_bf16 v[56:59], v[154:157], v[184:187], v[56:59]
	v_mfma_f32_16x16x32_bf16 v[44:47], v[140:143], v[192:195], v[44:47]
	v_mfma_f32_16x16x32_bf16 v[40:43], v[154:157], v[192:195], v[40:43]
	v_mfma_f32_16x16x32_bf16 v[28:31], v[140:143], v[222:225], v[28:31]
	v_mfma_f32_16x16x32_bf16 v[24:27], v[154:157], v[222:225], v[24:27]
	v_mfma_f32_16x16x32_bf16 v[12:15], v[140:143], v[230:233], v[12:15]
	v_mfma_f32_16x16x32_bf16 v[8:11], v[154:157], v[230:233], v[8:11]
	v_mfma_f32_16x16x32_bf16 v[60:63], v[150:153], v[188:191], v[60:63]
	v_mfma_f32_16x16x32_bf16 v[56:59], v[164:167], v[188:191], v[56:59]
	v_mfma_f32_16x16x32_bf16 v[44:47], v[150:153], v[196:199], v[44:47]
	v_mfma_f32_16x16x32_bf16 v[40:43], v[164:167], v[196:199], v[40:43]
	v_mfma_f32_16x16x32_bf16 v[28:31], v[150:153], v[226:229], v[28:31]
	v_mfma_f32_16x16x32_bf16 v[24:27], v[164:167], v[226:229], v[24:27]
	v_mfma_f32_16x16x32_bf16 v[12:15], v[150:153], v[234:237], v[12:15]
	v_mfma_f32_16x16x32_bf16 v[8:11], v[164:167], v[234:237], v[8:11]
	v_mfma_f32_16x16x32_bf16 v[52:55], v[168:171], v[184:187], v[52:55]
	v_mfma_f32_16x16x32_bf16 v[48:51], v[176:179], v[184:187], v[48:51]
	v_mfma_f32_16x16x32_bf16 v[36:39], v[168:171], v[192:195], v[36:39]
	v_mfma_f32_16x16x32_bf16 v[32:35], v[176:179], v[192:195], v[32:35]
	v_mfma_f32_16x16x32_bf16 v[20:23], v[168:171], v[222:225], v[20:23]
	v_mfma_f32_16x16x32_bf16 v[16:19], v[176:179], v[222:225], v[16:19]
	v_mfma_f32_16x16x32_bf16 v[4:7], v[168:171], v[230:233], v[4:7]
	v_mfma_f32_16x16x32_bf16 v[0:3], v[176:179], v[230:233], v[0:3]
	v_mfma_f32_16x16x32_bf16 v[52:55], v[172:175], v[188:191], v[52:55]
	v_mfma_f32_16x16x32_bf16 v[48:51], v[180:183], v[188:191], v[48:51]
	v_mfma_f32_16x16x32_bf16 v[36:39], v[172:175], v[196:199], v[36:39]
	v_mfma_f32_16x16x32_bf16 v[32:35], v[180:183], v[196:199], v[32:35]
	v_mfma_f32_16x16x32_bf16 v[20:23], v[172:175], v[226:229], v[20:23]
	v_mfma_f32_16x16x32_bf16 v[16:19], v[180:183], v[226:229], v[16:19]
	v_mfma_f32_16x16x32_bf16 v[4:7], v[172:175], v[234:237], v[4:7]
	v_mfma_f32_16x16x32_bf16 v[0:3], v[180:183], v[234:237], v[0:3]
	s_barrier
	s_add_i32 s87, s87, 2
	s_add_u32 s82, s82, 0x100
	s_addc_u32 s83, s83, 0
	s_add_u32 s29, s29, 0x100
	s_addc_u32 s43, s43, 0
	s_cmp_gt_u32 s87, 13
	s_cbranch_scc0 .LBB0_86
	s_and_b64 vcc, exec, s[12:13]
	s_cbranch_vccz .LBB0_89
	s_barrier

; #define PG8_STAGE(bufoff, gbase, voff) do { _Pragma("unroll") for (int _i = 0; _i < 2; ++_i) \
;         __builtin_amdgcn_global_load_lds((const unsigned*)((const char*)(gbase) + (voff)[_i]), (PG8_LAS unsigned*)(lds + (bufoff) + ldsw + _i * 8192), 16, 0, 0); } while (0)
; #define PG8_LDA(dst, b, h) do { _Pragma("unroll") for (int m = 0; m < 4; ++m) _Pragma("unroll") for (int k = 0; k < 2; ++k) dst[m][k] = *(const PG8_LAS bf16x8*)(lds + PG8_SA(b, h) + aoff + m * 2048 + k * 1024); } while (0)
; #define PG8_LDB(dst, b, h) do { _Pragma("unroll") for (int n = 0; n < 2; ++n) _Pragma("unroll") for (int k = 0; k < 2; ++k) dst[n][k] = *(const PG8_LAS bf16x8*)(lds + PG8_SB(b, h) + boff + n * 2048 + k * 1024); } while (0)
; #define PG8_SCHED __builtin_amdgcn_sched_barrier(0)
; template <class Epi, class Sched, bool ALIGN_EPI = false, bool SP2 = false>
; __device__ __forceinline__ void gemm_phase(PG8_LAS unsigned char* lds, const Gemm g, const Sched& S, const Epi& E) {
;     ...
;             const char* a1 = cA + (size_t)(t + 1) * kstep;
;             const char* a2 = last ? nA : cA + (size_t)(t + 2) * kstep; const char* b2 = last ? nB : cB + (size_t)(t + 2) * kstep;
;             const char* a3 = a2 + kstep; const char* b3 = b2 + kstep;
;             if (last && has_next) S.a_ready(nxt);
;             if constexpr (SP2) {
;             PG8_LDB(B0, 0, 0); PG8_LDB(B1, 0, 1); PG8_SCHED; PG8_LDA(At, 0, 0); PG8_STAGE(PG8_SA(1, 1), a1 + hstep, voffA);
.LBB0_322:
	s_add_i32 s56, 0, 0x10000
	s_add_i32 vcc_lo, 0, 0x14000
	s_waitcnt lgkmcnt(0)
	ds_read_b128 v[154:157], v246
	ds_read_b128 v[164:167], v246 offset:1024
	ds_read_b128 v[168:171], v246 offset:2048
	ds_read_b128 v[172:175], v246 offset:3072
	ds_read_b128 v[176:179], v246 offset:16384
	ds_read_b128 v[180:183], v246 offset:17408
	ds_read_b128 v[184:187], v246 offset:18432
	ds_read_b128 v[188:191], v246 offset:19456
	s_add_i32 m0, s89, 0xc000
	ds_read_b128 v[192:195], v145
	ds_read_b128 v[196:199], v145 offset:1024
	ds_read_b128 v[222:225], v145 offset:2048
	ds_read_b128 v[226:229], v145 offset:3072
	ds_read_b128 v[230:233], v145 offset:4096
	ds_read_b128 v[234:237], v145 offset:5120
	ds_read_b128 v[238:241], v145 offset:6144
	global_load_lds_dwordx4 v150, s[14:15]
	s_add_i32 m0, s89, 0xe000
	ds_read_b128 v[242:245], v145 offset:7168
	global_load_lds_dwordx4 v152, s[14:15]
	s_add_u32 s4, s14, 0xfff80080
	s_addc_u32 s5, s15, -1
	s_cmp_eq_u32 s55, 28
	s_cselect_b32 s53, s1, s5
	s_cselect_b32 s52, s28, s4
	s_cselect_b32 s5, s29, s54
	s_cselect_b32 s4, s43, s45

; #define PG8_STAGE(bufoff, gbase, voff) do { _Pragma("unroll") for (int _i = 0; _i < 2; ++_i) \
;         __builtin_amdgcn_global_load_lds((const unsigned*)((const char*)(gbase) + (voff)[_i]), (PG8_LAS unsigned*)(lds + (bufoff) + ldsw + _i * 8192), 16, 0, 0); } while (0)
; #define PG8_LDA(dst, b, h) do { _Pragma("unroll") for (int m = 0; m < 4; ++m) _Pragma("unroll") for (int k = 0; k < 2; ++k) dst[m][k] = *(const PG8_LAS bf16x8*)(lds + PG8_SA(b, h) + aoff + m * 2048 + k * 1024); } while (0)
; #define PG8_MMA(ai, bj, At, Bt) do { __builtin_amdgcn_s_setprio(1); _Pragma("unroll") for (int m = 0; m < 4; ++m) _Pragma("unroll") for (int n = 0; n < 2; ++n) _Pragma("unroll") for (int k = 0; k < 2; ++k) \
;         acc[ai][bj][m][n] = __builtin_amdgcn_mfma_f32_16x16x32_bf16(Bt[n][k], At[m][k], acc[ai][bj][m][n], 0, 0, 0); __builtin_amdgcn_s_setprio(0); } while (0)
; #define PG8_WAIT_V(n) asm volatile("s_waitcnt vmcnt(" #n ")" ::: "memory")
; #define PG8_WAIT_L(n) asm volatile("s_waitcnt lgkmcnt(" #n ")" ::: "memory")
; #define PG8_BAR __builtin_amdgcn_s_barrier()
; #define PG8_SCHED __builtin_amdgcn_sched_barrier(0)
; template <class Epi, class Sched, bool ALIGN_EPI = false, bool SP2 = false>
; __device__ __forceinline__ void gemm_phase(PG8_LAS unsigned char* lds, const Gemm g, const Sched& S, const Epi& E) {
;     ...
;             PG8_WAIT_V(8); PG8_WAIT_L(0); PG8_BAR; PG8_MMA(0, 0, At, B0); PG8_MMA(0, 1, At, B1); PG8_BAR; PG8_SCHED;
;             PG8_LDA(At, 0, 1); PG8_STAGE(PG8_SB(0, 0), b2, voffB); PG8_STAGE(PG8_SB(0, 1), b2 + hstep, voffB); PG8_STAGE(PG8_SA(0, 0), a2, voffA);
	s_waitcnt vmcnt(8)
	s_waitcnt lgkmcnt(0)
	s_barrier
	s_waitcnt lgkmcnt(0)
	v_mfma_f32_16x16x32_bf16 v[124:127], v[154:157], v[192:195], v[124:127]
	v_mfma_f32_16x16x32_bf16 v[120:123], v[168:171], v[192:195], v[120:123]
	v_mfma_f32_16x16x32_bf16 v[116:119], v[154:157], v[222:225], v[116:119]
	v_mfma_f32_16x16x32_bf16 v[112:115], v[168:171], v[222:225], v[112:115]
	v_mfma_f32_16x16x32_bf16 v[108:111], v[154:157], v[230:233], v[108:111]
	v_mfma_f32_16x16x32_bf16 v[104:107], v[168:171], v[230:233], v[104:107]
	v_mfma_f32_16x16x32_bf16 v[100:103], v[154:157], v[238:241], v[100:103]
	v_mfma_f32_16x16x32_bf16 v[96:99], v[168:171], v[238:241], v[96:99]
	v_mfma_f32_16x16x32_bf16 v[124:127], v[164:167], v[196:199], v[124:127]
	v_mfma_f32_16x16x32_bf16 v[120:123], v[172:175], v[196:199], v[120:123]
	v_mfma_f32_16x16x32_bf16 v[116:119], v[164:167], v[226:229], v[116:119]
	v_mfma_f32_16x16x32_bf16 v[112:115], v[172:175], v[226:229], v[112:115]
	v_mfma_f32_16x16x32_bf16 v[108:111], v[164:167], v[234:237], v[108:111]
	v_mfma_f32_16x16x32_bf16 v[104:107], v[172:175], v[234:237], v[104:107]
	v_mfma_f32_16x16x32_bf16 v[100:103], v[164:167], v[242:245], v[100:103]
	v_mfma_f32_16x16x32_bf16 v[96:99], v[172:175], v[242:245], v[96:99]
	v_mfma_f32_16x16x32_bf16 v[92:95], v[176:179], v[192:195], v[92:95]
	v_mfma_f32_16x16x32_bf16 v[88:91], v[184:187], v[192:195], v[88:91]
	v_mfma_f32_16x16x32_bf16 v[84:87], v[176:179], v[222:225], v[84:87]
	v_mfma_f32_16x16x32_bf16 v[80:83], v[184:187], v[222:225], v[80:83]
	v_mfma_f32_16x16x32_bf16 v[76:79], v[176:179], v[230:233], v[76:79]
	v_mfma_f32_16x16x32_bf16 v[72:75], v[184:187], v[230:233], v[72:75]
	v_mfma_f32_16x16x32_bf16 v[68:71], v[176:179], v[238:241], v[68:71]
	v_mfma_f32_16x16x32_bf16 v[64:67], v[184:187], v[238:241], v[64:67]
	v_mfma_f32_16x16x32_bf16 v[92:95], v[180:183], v[196:199], v[92:95]
	v_mfma_f32_16x16x32_bf16 v[88:91], v[188:191], v[196:199], v[88:91]
	v_mfma_f32_16x16x32_bf16 v[84:87], v[180:183], v[226:229], v[84:87]
	v_mfma_f32_16x16x32_bf16 v[80:83], v[188:191], v[226:229], v[80:83]
	v_mfma_f32_16x16x32_bf16 v[76:79], v[180:183], v[234:237], v[76:79]
	v_mfma_f32_16x16x32_bf16 v[72:75], v[188:191], v[234:237], v[72:75]
	v_mfma_f32_16x16x32_bf16 v[68:71], v[180:183], v[242:245], v[68:71]
	v_mfma_f32_16x16x32_bf16 v[64:67], v[188:191], v[242:245], v[64:67]
	s_barrier
	s_add_i32 s56, s56, s63
	s_mov_b32 m0, s56
	ds_read_b128 v[192:195], v145 offset:16384
	ds_read_b128 v[196:199], v145 offset:17408
	ds_read_b128 v[222:225], v145 offset:18432
	ds_read_b128 v[226:229], v145 offset:19456
	global_load_lds_dwordx4 v130, s[4:5]
	s_add_i32 m0, s56, 0x2000
	s_add_u32 s56, s4, 0x80000
	s_addc_u32 s57, s5, 0
	s_add_i32 vcc_lo, vcc_lo, s63
	global_load_lds_dwordx4 v134, s[4:5]
	s_mov_b32 m0, vcc_lo
	ds_read_b128 v[230:233], v145 offset:20480
	global_load_lds_dwordx4 v130, s[56:57]
	s_add_i32 m0, vcc_lo, 0x2000
	ds_read_b128 v[234:237], v145 offset:21504
	global_load_lds_dwordx4 v134, s[56:57]
	s_mov_b32 m0, s89
	ds_read_b128 v[238:241], v145 offset:22528
	global_load_lds_dwordx4 v128, s[52:53]
	s_mov_b32 m0, s91
	ds_read_b128 v[242:245], v145 offset:23552
	global_load_lds_dwordx4 v132, s[52:53]
	s_add_u32 s98, s52, 0x80
	s_addc_u32 s99, s53, 0


; #define PG8_STAGE(bufoff, gbase, voff) do { _Pragma("unroll") for (int _i = 0; _i < 2; ++_i) \
;         __builtin_amdgcn_global_load_lds((const unsigned*)((const char*)(gbase) + (voff)[_i]), (PG8_LAS unsigned*)(lds + (bufoff) + ldsw + _i * 8192), 16, 0, 0); } while (0)
; #define PG8_LDA(dst, b, h) do { _Pragma("unroll") for (int m = 0; m < 4; ++m) _Pragma("unroll") for (int k = 0; k < 2; ++k) dst[m][k] = *(const PG8_LAS bf16x8*)(lds + PG8_SA(b, h) + aoff + m * 2048 + k * 1024); } while (0)
; #define PG8_LDB(dst, b, h) do { _Pragma("unroll") for (int n = 0; n < 2; ++n) _Pragma("unroll") for (int k = 0; k < 2; ++k) dst[n][k] = *(const PG8_LAS bf16x8*)(lds + PG8_SB(b, h) + boff + n * 2048 + k * 1024); } while (0)
; #define PG8_MMA(ai, bj, At, Bt) do { __builtin_amdgcn_s_setprio(1); _Pragma("unroll") for (int m = 0; m < 4; ++m) _Pragma("unroll") for (int n = 0; n < 2; ++n) _Pragma("unroll") for (int k = 0; k < 2; ++k) \
;         acc[ai][bj][m][n] = __builtin_amdgcn_mfma_f32_16x16x32_bf16(Bt[n][k], At[m][k], acc[ai][bj][m][n], 0, 0, 0); __builtin_amdgcn_s_setprio(0); } while (0)
; #define PG8_WAIT_V(n) asm volatile("s_waitcnt vmcnt(" #n ")" ::: "memory")
; #define PG8_WAIT_L(n) asm volatile("s_waitcnt lgkmcnt(" #n ")" ::: "memory")
; #define PG8_BAR __builtin_amdgcn_s_barrier()
; #define PG8_SCHED __builtin_amdgcn_sched_barrier(0)
; template <class Epi, class Sched, bool ALIGN_EPI = false, bool SP2 = false>
; __device__ __forceinline__ void gemm_phase(PG8_LAS unsigned char* lds, const Gemm g, const Sched& S, const Epi& E) {
;     ...
;             PG8_WAIT_V(8); PG8_WAIT_L(0); PG8_BAR; PG8_MMA(1, 0, At, B0); PG8_MMA(1, 1, At, B1); PG8_BAR; PG8_SCHED;
;             PG8_LDB(B0, 1, 0); PG8_LDB(B1, 1, 1); PG8_SCHED; PG8_LDA(At, 1, 0); PG8_STAGE(PG8_SA(0, 1), a2 + hstep, voffA);
	s_waitcnt vmcnt(8)
	s_waitcnt lgkmcnt(0)
	s_barrier
	s_waitcnt lgkmcnt(0)
	v_mfma_f32_16x16x32_bf16 v[60:63], v[154:157], v[192:195], v[60:63]
	v_mfma_f32_16x16x32_bf16 v[56:59], v[168:171], v[192:195], v[56:59]
	v_mfma_f32_16x16x32_bf16 v[52:55], v[154:157], v[222:225], v[52:55]
	v_mfma_f32_16x16x32_bf16 v[48:51], v[168:171], v[222:225], v[48:51]
	v_mfma_f32_16x16x32_bf16 v[44:47], v[154:157], v[230:233], v[44:47]
	v_mfma_f32_16x16x32_bf16 v[40:43], v[168:171], v[230:233], v[40:43]
	v_mfma_f32_16x16x32_bf16 v[36:39], v[154:157], v[238:241], v[36:39]
	v_mfma_f32_16x16x32_bf16 v[32:35], v[168:171], v[238:241], v[32:35]
	v_mfma_f32_16x16x32_bf16 v[60:63], v[164:167], v[196:199], v[60:63]
	v_mfma_f32_16x16x32_bf16 v[56:59], v[172:175], v[196:199], v[56:59]
	v_mfma_f32_16x16x32_bf16 v[52:55], v[164:167], v[226:229], v[52:55]
	v_mfma_f32_16x16x32_bf16 v[48:51], v[172:175], v[226:229], v[48:51]
	v_mfma_f32_16x16x32_bf16 v[44:47], v[164:167], v[234:237], v[44:47]
	v_mfma_f32_16x16x32_bf16 v[40:43], v[172:175], v[234:237], v[40:43]
	v_mfma_f32_16x16x32_bf16 v[36:39], v[164:167], v[242:245], v[36:39]
	v_mfma_f32_16x16x32_bf16 v[32:35], v[172:175], v[242:245], v[32:35]
	v_mfma_f32_16x16x32_bf16 v[28:31], v[176:179], v[192:195], v[28:31]
	v_mfma_f32_16x16x32_bf16 v[24:27], v[184:187], v[192:195], v[24:27]
	v_mfma_f32_16x16x32_bf16 v[20:23], v[176:179], v[222:225], v[20:23]
	v_mfma_f32_16x16x32_bf16 v[16:19], v[184:187], v[222:225], v[16:19]
	v_mfma_f32_16x16x32_bf16 v[12:15], v[176:179], v[230:233], v[12:15]
	v_mfma_f32_16x16x32_bf16 v[8:11], v[184:187], v[230:233], v[8:11]
	v_mfma_f32_16x16x32_bf16 v[4:7], v[176:179], v[238:241], v[4:7]
	v_mfma_f32_16x16x32_bf16 v[0:3], v[184:187], v[238:241], v[0:3]
	v_mfma_f32_16x16x32_bf16 v[28:31], v[180:183], v[196:199], v[28:31]
	v_mfma_f32_16x16x32_bf16 v[24:27], v[188:191], v[196:199], v[24:27]
	v_mfma_f32_16x16x32_bf16 v[20:23], v[180:183], v[226:229], v[20:23]
	v_mfma_f32_16x16x32_bf16 v[16:19], v[188:191], v[226:229], v[16:19]
	v_mfma_f32_16x16x32_bf16 v[12:15], v[180:183], v[234:237], v[12:15]
	v_mfma_f32_16x16x32_bf16 v[8:11], v[188:191], v[234:237], v[8:11]
	v_mfma_f32_16x16x32_bf16 v[4:7], v[180:183], v[242:245], v[4:7]
	v_mfma_f32_16x16x32_bf16 v[0:3], v[188:191], v[242:245], v[0:3]
	s_barrier
	s_add_i32 s56, 0, 0x18000
	s_add_i32 s57, 0, 0x1c000
	ds_read_b128 v[154:157], v246 offset:32768
	ds_read_b128 v[164:167], v246 offset:33792
	ds_read_b128 v[168:171], v246 offset:34816
	ds_read_b128 v[172:175], v246 offset:35840
	ds_read_b128 v[176:179], v246 offset:49152
	ds_read_b128 v[180:183], v246 offset:50176
	ds_read_b128 v[184:187], v246 offset:51200
	ds_read_b128 v[188:191], v246 offset:52224
	s_add_u32 s52, s52, 0x80000
	s_addc_u32 s53, s53, 0
	s_mov_b32 m0, s12
	ds_read_b128 v[192:195], v145 offset:32768
	ds_read_b128 v[196:199], v145 offset:33792
	ds_read_b128 v[222:225], v145 offset:34816
	ds_read_b128 v[226:229], v145 offset:35840
	ds_read_b128 v[230:233], v145 offset:36864
	ds_read_b128 v[234:237], v145 offset:37888
	ds_read_b128 v[238:241], v145 offset:38912
	global_load_lds_dwordx4 v128, s[52:53]
	s_mov_b32 m0, s13
	ds_read_b128 v[242:245], v145 offset:39936
	global_load_lds_dwordx4 v132, s[52:53]

; #define PG8_STAGE(bufoff, gbase, voff) do { _Pragma("unroll") for (int _i = 0; _i < 2; ++_i) \
;         __builtin_amdgcn_global_load_lds((const unsigned*)((const char*)(gbase) + (voff)[_i]), (PG8_LAS unsigned*)(lds + (bufoff) + ldsw + _i * 8192), 16, 0, 0); } while (0)
; #define PG8_LDA(dst, b, h) do { _Pragma("unroll") for (int m = 0; m < 4; ++m) _Pragma("unroll") for (int k = 0; k < 2; ++k) dst[m][k] = *(const PG8_LAS bf16x8*)(lds + PG8_SA(b, h) + aoff + m * 2048 + k * 1024); } while (0)
; #define PG8_MMA(ai, bj, At, Bt) do { __builtin_amdgcn_s_setprio(1); _Pragma("unroll") for (int m = 0; m < 4; ++m) _Pragma("unroll") for (int n = 0; n < 2; ++n) _Pragma("unroll") for (int k = 0; k < 2; ++k) \
;         acc[ai][bj][m][n] = __builtin_amdgcn_mfma_f32_16x16x32_bf16(Bt[n][k], At[m][k], acc[ai][bj][m][n], 0, 0, 0); __builtin_amdgcn_s_setprio(0); } while (0)
; #define PG8_WAIT_V(n) asm volatile("s_waitcnt vmcnt(" #n ")" ::: "memory")
; #define PG8_WAIT_L(n) asm volatile("s_waitcnt lgkmcnt(" #n ")" ::: "memory")
; #define PG8_BAR __builtin_amdgcn_s_barrier()
; #define PG8_SCHED __builtin_amdgcn_sched_barrier(0)
; template <class Epi, class Sched, bool ALIGN_EPI = false, bool SP2 = false>
; __device__ __forceinline__ void gemm_phase(PG8_LAS unsigned char* lds, const Gemm g, const Sched& S, const Epi& E) {
;     ...
;             PG8_WAIT_V(8); PG8_WAIT_L(0); PG8_BAR; PG8_MMA(0, 0, At, B0); PG8_MMA(0, 1, At, B1); PG8_BAR; PG8_SCHED;
;             PG8_LDA(At, 1, 1); PG8_STAGE(PG8_SB(1, 0), b3, voffB); PG8_STAGE(PG8_SB(1, 1), b3 + hstep, voffB); PG8_STAGE(PG8_SA(1, 0), a3, voffA);
	s_waitcnt vmcnt(8)
	s_waitcnt lgkmcnt(0)
	s_barrier
	s_waitcnt lgkmcnt(0)
	v_mfma_f32_16x16x32_bf16 v[124:127], v[154:157], v[192:195], v[124:127]
	v_mfma_f32_16x16x32_bf16 v[120:123], v[168:171], v[192:195], v[120:123]
	v_mfma_f32_16x16x32_bf16 v[116:119], v[154:157], v[222:225], v[116:119]
	v_mfma_f32_16x16x32_bf16 v[112:115], v[168:171], v[222:225], v[112:115]
	v_mfma_f32_16x16x32_bf16 v[108:111], v[154:157], v[230:233], v[108:111]
	v_mfma_f32_16x16x32_bf16 v[104:107], v[168:171], v[230:233], v[104:107]
	v_mfma_f32_16x16x32_bf16 v[100:103], v[154:157], v[238:241], v[100:103]
	v_mfma_f32_16x16x32_bf16 v[96:99], v[168:171], v[238:241], v[96:99]
	v_mfma_f32_16x16x32_bf16 v[124:127], v[164:167], v[196:199], v[124:127]
	v_mfma_f32_16x16x32_bf16 v[120:123], v[172:175], v[196:199], v[120:123]
	v_mfma_f32_16x16x32_bf16 v[116:119], v[164:167], v[226:229], v[116:119]
	v_mfma_f32_16x16x32_bf16 v[112:115], v[172:175], v[226:229], v[112:115]
	v_mfma_f32_16x16x32_bf16 v[108:111], v[164:167], v[234:237], v[108:111]
	v_mfma_f32_16x16x32_bf16 v[104:107], v[172:175], v[234:237], v[104:107]
	v_mfma_f32_16x16x32_bf16 v[100:103], v[164:167], v[242:245], v[100:103]
	v_mfma_f32_16x16x32_bf16 v[96:99], v[172:175], v[242:245], v[96:99]
	v_mfma_f32_16x16x32_bf16 v[92:95], v[176:179], v[192:195], v[92:95]
	v_mfma_f32_16x16x32_bf16 v[88:91], v[184:187], v[192:195], v[88:91]
	v_mfma_f32_16x16x32_bf16 v[84:87], v[176:179], v[222:225], v[84:87]
	v_mfma_f32_16x16x32_bf16 v[80:83], v[184:187], v[222:225], v[80:83]
	v_mfma_f32_16x16x32_bf16 v[76:79], v[176:179], v[230:233], v[76:79]
	v_mfma_f32_16x16x32_bf16 v[72:75], v[184:187], v[230:233], v[72:75]
	v_mfma_f32_16x16x32_bf16 v[68:71], v[176:179], v[238:241], v[68:71]
	v_mfma_f32_16x16x32_bf16 v[64:67], v[184:187], v[238:241], v[64:67]
	v_mfma_f32_16x16x32_bf16 v[92:95], v[180:183], v[196:199], v[92:95]
	v_mfma_f32_16x16x32_bf16 v[88:91], v[188:191], v[196:199], v[88:91]
	v_mfma_f32_16x16x32_bf16 v[84:87], v[180:183], v[226:229], v[84:87]
	v_mfma_f32_16x16x32_bf16 v[80:83], v[188:191], v[226:229], v[80:83]
	v_mfma_f32_16x16x32_bf16 v[76:79], v[180:183], v[234:237], v[76:79]
	v_mfma_f32_16x16x32_bf16 v[72:75], v[188:191], v[234:237], v[72:75]
	v_mfma_f32_16x16x32_bf16 v[68:71], v[180:183], v[242:245], v[68:71]
	v_mfma_f32_16x16x32_bf16 v[64:67], v[188:191], v[242:245], v[64:67]
	s_barrier
	s_add_i32 s52, s56, s63
	s_mov_b32 m0, s52
	ds_read_b128 v[192:195], v145 offset:49152
	ds_read_b128 v[196:199], v145 offset:50176
	ds_read_b128 v[222:225], v145 offset:51200
	ds_read_b128 v[226:229], v145 offset:52224
	s_add_u32 s4, s4, 0x80
	s_addc_u32 s5, s5, 0
	global_load_lds_dwordx4 v130, s[4:5]
	s_add_i32 m0, s52, 0x2000
	s_add_i32 s52, s57, s63
	global_load_lds_dwordx4 v134, s[4:5]
	s_add_u32 s4, s4, 0x80000
	s_addc_u32 s5, s5, 0
	s_mov_b32 m0, s52
	ds_read_b128 v[230:233], v145 offset:53248
	global_load_lds_dwordx4 v130, s[4:5]
	s_add_i32 m0, s52, 0x2000
	ds_read_b128 v[234:237], v145 offset:54272
	global_load_lds_dwordx4 v134, s[4:5]
	s_mov_b32 m0, s78
	ds_read_b128 v[238:241], v145 offset:55296
	global_load_lds_dwordx4 v128, s[98:99]
	s_mov_b32 m0, s79
	ds_read_b128 v[242:245], v145 offset:56320
	global_load_lds_dwordx4 v132, s[98:99]


; #define PG8_MMA(ai, bj, At, Bt) do { __builtin_amdgcn_s_setprio(1); _Pragma("unroll") for (int m = 0; m < 4; ++m) _Pragma("unroll") for (int n = 0; n < 2; ++n) _Pragma("unroll") for (int k = 0; k < 2; ++k) \
;         acc[ai][bj][m][n] = __builtin_amdgcn_mfma_f32_16x16x32_bf16(Bt[n][k], At[m][k], acc[ai][bj][m][n], 0, 0, 0); __builtin_amdgcn_s_setprio(0); } while (0)
; #define PG8_WAIT_V(n) asm volatile("s_waitcnt vmcnt(" #n ")" ::: "memory")
; #define PG8_WAIT_L(n) asm volatile("s_waitcnt lgkmcnt(" #n ")" ::: "memory")
; #define PG8_BAR __builtin_amdgcn_s_barrier()
; #define PG8_SCHED __builtin_amdgcn_sched_barrier(0)
; template <class Epi, class Sched, bool ALIGN_EPI = false, bool SP2 = false>
; __device__ __forceinline__ void gemm_phase(PG8_LAS unsigned char* lds, const Gemm g, const Sched& S, const Epi& E) {
;     ...
;         for (int t = 0; t < nt; t += 2) {
;     ...
;             PG8_WAIT_V(8); PG8_WAIT_L(0); PG8_BAR; PG8_MMA(1, 0, At, B0); PG8_MMA(1, 1, At, B1); PG8_BAR; PG8_SCHED;
	s_waitcnt vmcnt(8)
	s_waitcnt lgkmcnt(0)
	s_barrier
	s_waitcnt lgkmcnt(0)
	v_mfma_f32_16x16x32_bf16 v[60:63], v[154:157], v[192:195], v[60:63]
	v_mfma_f32_16x16x32_bf16 v[56:59], v[168:171], v[192:195], v[56:59]
	v_mfma_f32_16x16x32_bf16 v[52:55], v[154:157], v[222:225], v[52:55]
	v_mfma_f32_16x16x32_bf16 v[48:51], v[168:171], v[222:225], v[48:51]
	v_mfma_f32_16x16x32_bf16 v[44:47], v[154:157], v[230:233], v[44:47]
	v_mfma_f32_16x16x32_bf16 v[40:43], v[168:171], v[230:233], v[40:43]
	v_mfma_f32_16x16x32_bf16 v[36:39], v[154:157], v[238:241], v[36:39]
	v_mfma_f32_16x16x32_bf16 v[32:35], v[168:171], v[238:241], v[32:35]
	v_mfma_f32_16x16x32_bf16 v[60:63], v[164:167], v[196:199], v[60:63]
	v_mfma_f32_16x16x32_bf16 v[56:59], v[172:175], v[196:199], v[56:59]
	v_mfma_f32_16x16x32_bf16 v[52:55], v[164:167], v[226:229], v[52:55]
	v_mfma_f32_16x16x32_bf16 v[48:51], v[172:175], v[226:229], v[48:51]
	v_mfma_f32_16x16x32_bf16 v[44:47], v[164:167], v[234:237], v[44:47]
	v_mfma_f32_16x16x32_bf16 v[40:43], v[172:175], v[234:237], v[40:43]
	v_mfma_f32_16x16x32_bf16 v[36:39], v[164:167], v[242:245], v[36:39]
	v_mfma_f32_16x16x32_bf16 v[32:35], v[172:175], v[242:245], v[32:35]
	v_mfma_f32_16x16x32_bf16 v[28:31], v[176:179], v[192:195], v[28:31]
	v_mfma_f32_16x16x32_bf16 v[24:27], v[184:187], v[192:195], v[24:27]
	v_mfma_f32_16x16x32_bf16 v[20:23], v[176:179], v[222:225], v[20:23]
	v_mfma_f32_16x16x32_bf16 v[16:19], v[184:187], v[222:225], v[16:19]
	v_mfma_f32_16x16x32_bf16 v[12:15], v[176:179], v[230:233], v[12:15]
	v_mfma_f32_16x16x32_bf16 v[8:11], v[184:187], v[230:233], v[8:11]
	v_mfma_f32_16x16x32_bf16 v[4:7], v[176:179], v[238:241], v[4:7]
	v_mfma_f32_16x16x32_bf16 v[0:3], v[184:187], v[238:241], v[0:3]
	v_mfma_f32_16x16x32_bf16 v[28:31], v[180:183], v[196:199], v[28:31]
	v_mfma_f32_16x16x32_bf16 v[24:27], v[188:191], v[196:199], v[24:27]
	v_mfma_f32_16x16x32_bf16 v[20:23], v[180:183], v[226:229], v[20:23]
	v_mfma_f32_16x16x32_bf16 v[16:19], v[188:191], v[226:229], v[16:19]
	v_mfma_f32_16x16x32_bf16 v[12:15], v[180:183], v[234:237], v[12:15]
	v_mfma_f32_16x16x32_bf16 v[8:11], v[188:191], v[234:237], v[8:11]
	v_mfma_f32_16x16x32_bf16 v[4:7], v[180:183], v[242:245], v[4:7]
	v_mfma_f32_16x16x32_bf16 v[0:3], v[188:191], v[242:245], v[0:3]
	s_barrier
	s_add_i32 s55, s55, 2
	s_add_u32 s14, s14, 0x100
	s_addc_u32 s15, s15, 0
	s_add_u32 s45, s45, 0x100
	s_addc_u32 s54, s54, 0
	s_cmp_gt_u32 s55, 29
	s_cbranch_scc0 .LBB0_322
	s_and_b64 vcc, exec, s[82:83]
	s_cbranch_vccz .LBB0_325
	s_barrier

; #define PG8_STAGE(bufoff, gbase, voff) do { _Pragma("unroll") for (int _i = 0; _i < 2; ++_i) \
;         __builtin_amdgcn_global_load_lds((const unsigned*)((const char*)(gbase) + (voff)[_i]), (PG8_LAS unsigned*)(lds + (bufoff) + ldsw + _i * 8192), 16, 0, 0); } while (0)
; #define PG8_LDA(dst, b, h) do { _Pragma("unroll") for (int m = 0; m < 4; ++m) _Pragma("unroll") for (int k = 0; k < 2; ++k) dst[m][k] = *(const PG8_LAS bf16x8*)(lds + PG8_SA(b, h) + aoff + m * 2048 + k * 1024); } while (0)
; #define PG8_LDB(dst, b, h) do { _Pragma("unroll") for (int n = 0; n < 2; ++n) _Pragma("unroll") for (int k = 0; k < 2; ++k) dst[n][k] = *(const PG8_LAS bf16x8*)(lds + PG8_SB(b, h) + boff + n * 2048 + k * 1024); } while (0)
; #define PG8_SCHED __builtin_amdgcn_sched_barrier(0)
; template <class Epi, class Sched, bool ALIGN_EPI = false, bool SP2 = false>
; __device__ __forceinline__ void gemm_phase(PG8_LAS unsigned char* lds, const Gemm g, const Sched& S, const Epi& E) {
;     ...
;             const char* a1 = cA + (size_t)(t + 1) * kstep;
;             const char* a2 = last ? nA : cA + (size_t)(t + 2) * kstep; const char* b2 = last ? nB : cB + (size_t)(t + 2) * kstep;
;             const char* a3 = a2 + kstep; const char* b3 = b2 + kstep;
;             if (last && has_next) S.a_ready(nxt);
;             if constexpr (SP2) {
;             PG8_LDB(B0, 0, 0); PG8_LDB(B1, 0, 1); PG8_SCHED; PG8_LDA(At, 0, 0); PG8_STAGE(PG8_SA(1, 1), a1 + hstep, voffA);
.LBB0_849:
	s_add_i32 s76, 0, 0x10000
	s_add_i32 s78, 0, 0x14000
	ds_read_b128 v[144:147], v200
	ds_read_b128 v[148:151], v200 offset:1024
	ds_read_b128 v[152:155], v200 offset:2048
	ds_read_b128 v[156:159], v200 offset:3072
	ds_read_b128 v[164:167], v200 offset:16384
	ds_read_b128 v[168:171], v200 offset:17408
	ds_read_b128 v[172:175], v200 offset:18432
	ds_read_b128 v[176:179], v200 offset:19456
	s_add_i32 m0, s51, 0xc000
	ds_read_b128 v[180:183], v143
	ds_read_b128 v[184:187], v143 offset:1024
	ds_read_b128 v[188:191], v143 offset:2048
	ds_read_b128 v[192:195], v143 offset:3072
	ds_read_b128 v[196:199], v143 offset:4096
	ds_read_b128 v[222:225], v143 offset:5120
	ds_read_b128 v[226:229], v143 offset:6144
	global_load_lds_dwordx4 v134, s[70:71]
	s_add_i32 m0, s51, 0xe000
	ds_read_b128 v[230:233], v143 offset:7168
	global_load_lds_dwordx4 v136, s[70:71]
	s_add_u32 s4, s70, 0xfff80080
	s_addc_u32 s5, s71, -1
	s_cmp_eq_u32 s75, 28
	s_cselect_b32 s53, s11, s5
	s_cselect_b32 s52, s63, s4
	s_cselect_b32 s5, s13, s74
	s_cselect_b32 s4, s72, s73

; #define PG8_STAGE(bufoff, gbase, voff) do { _Pragma("unroll") for (int _i = 0; _i < 2; ++_i) \
;         __builtin_amdgcn_global_load_lds((const unsigned*)((const char*)(gbase) + (voff)[_i]), (PG8_LAS unsigned*)(lds + (bufoff) + ldsw + _i * 8192), 16, 0, 0); } while (0)
; #define PG8_LDA(dst, b, h) do { _Pragma("unroll") for (int m = 0; m < 4; ++m) _Pragma("unroll") for (int k = 0; k < 2; ++k) dst[m][k] = *(const PG8_LAS bf16x8*)(lds + PG8_SA(b, h) + aoff + m * 2048 + k * 1024); } while (0)
; #define PG8_MMA(ai, bj, At, Bt) do { __builtin_amdgcn_s_setprio(1); _Pragma("unroll") for (int m = 0; m < 4; ++m) _Pragma("unroll") for (int n = 0; n < 2; ++n) _Pragma("unroll") for (int k = 0; k < 2; ++k) \
;         acc[ai][bj][m][n] = __builtin_amdgcn_mfma_f32_16x16x32_bf16(Bt[n][k], At[m][k], acc[ai][bj][m][n], 0, 0, 0); __builtin_amdgcn_s_setprio(0); } while (0)
; #define PG8_WAIT_V(n) asm volatile("s_waitcnt vmcnt(" #n ")" ::: "memory")
; #define PG8_WAIT_L(n) asm volatile("s_waitcnt lgkmcnt(" #n ")" ::: "memory")
; #define PG8_BAR __builtin_amdgcn_s_barrier()
; #define PG8_SCHED __builtin_amdgcn_sched_barrier(0)
; template <class Epi, class Sched, bool ALIGN_EPI = false, bool SP2 = false>
; __device__ __forceinline__ void gemm_phase(PG8_LAS unsigned char* lds, const Gemm g, const Sched& S, const Epi& E) {
;     ...
;             PG8_WAIT_V(8); PG8_WAIT_L(0); PG8_BAR; PG8_MMA(0, 0, At, B0); PG8_MMA(0, 1, At, B1); PG8_BAR; PG8_SCHED;
;             PG8_LDA(At, 0, 1); PG8_STAGE(PG8_SB(0, 0), b2, voffB); PG8_STAGE(PG8_SB(0, 1), b2 + hstep, voffB); PG8_STAGE(PG8_SA(0, 0), a2, voffA);
	s_waitcnt vmcnt(8)
	s_waitcnt lgkmcnt(0)
	s_barrier
	s_waitcnt lgkmcnt(0)
	v_mfma_f32_16x16x32_bf16 v[124:127], v[144:147], v[180:183], v[124:127]
	v_mfma_f32_16x16x32_bf16 v[116:119], v[152:155], v[180:183], v[116:119]
	v_mfma_f32_16x16x32_bf16 v[108:111], v[144:147], v[188:191], v[108:111]
	v_mfma_f32_16x16x32_bf16 v[100:103], v[152:155], v[188:191], v[100:103]
	v_mfma_f32_16x16x32_bf16 v[92:95], v[144:147], v[196:199], v[92:95]
	v_mfma_f32_16x16x32_bf16 v[84:87], v[152:155], v[196:199], v[84:87]
	v_mfma_f32_16x16x32_bf16 v[76:79], v[144:147], v[226:229], v[76:79]
	v_mfma_f32_16x16x32_bf16 v[68:71], v[152:155], v[226:229], v[68:71]
	v_mfma_f32_16x16x32_bf16 v[124:127], v[148:151], v[184:187], v[124:127]
	v_mfma_f32_16x16x32_bf16 v[116:119], v[156:159], v[184:187], v[116:119]
	v_mfma_f32_16x16x32_bf16 v[108:111], v[148:151], v[192:195], v[108:111]
	v_mfma_f32_16x16x32_bf16 v[100:103], v[156:159], v[192:195], v[100:103]
	v_mfma_f32_16x16x32_bf16 v[92:95], v[148:151], v[222:225], v[92:95]
	v_mfma_f32_16x16x32_bf16 v[84:87], v[156:159], v[222:225], v[84:87]
	v_mfma_f32_16x16x32_bf16 v[76:79], v[148:151], v[230:233], v[76:79]
	v_mfma_f32_16x16x32_bf16 v[68:71], v[156:159], v[230:233], v[68:71]
	v_mfma_f32_16x16x32_bf16 v[120:123], v[164:167], v[180:183], v[120:123]
	v_mfma_f32_16x16x32_bf16 v[112:115], v[172:175], v[180:183], v[112:115]
	v_mfma_f32_16x16x32_bf16 v[104:107], v[164:167], v[188:191], v[104:107]
	v_mfma_f32_16x16x32_bf16 v[96:99], v[172:175], v[188:191], v[96:99]
	v_mfma_f32_16x16x32_bf16 v[88:91], v[164:167], v[196:199], v[88:91]
	v_mfma_f32_16x16x32_bf16 v[80:83], v[172:175], v[196:199], v[80:83]
	v_mfma_f32_16x16x32_bf16 v[72:75], v[164:167], v[226:229], v[72:75]
	v_mfma_f32_16x16x32_bf16 v[64:67], v[172:175], v[226:229], v[64:67]
	v_mfma_f32_16x16x32_bf16 v[120:123], v[168:171], v[184:187], v[120:123]
	v_mfma_f32_16x16x32_bf16 v[112:115], v[176:179], v[184:187], v[112:115]
	v_mfma_f32_16x16x32_bf16 v[104:107], v[168:171], v[192:195], v[104:107]
	v_mfma_f32_16x16x32_bf16 v[96:99], v[176:179], v[192:195], v[96:99]
	v_mfma_f32_16x16x32_bf16 v[88:91], v[168:171], v[222:225], v[88:91]
	v_mfma_f32_16x16x32_bf16 v[80:83], v[176:179], v[222:225], v[80:83]
	v_mfma_f32_16x16x32_bf16 v[72:75], v[168:171], v[230:233], v[72:75]
	v_mfma_f32_16x16x32_bf16 v[64:67], v[176:179], v[230:233], v[64:67]
	s_barrier
	s_add_i32 s76, s76, s24
	s_mov_b32 m0, s76
	ds_read_b128 v[180:183], v143 offset:16384
	ds_read_b128 v[184:187], v143 offset:17408
	ds_read_b128 v[188:191], v143 offset:18432
	ds_read_b128 v[192:195], v143 offset:19456
	global_load_lds_dwordx4 v160, s[4:5]
	s_add_i32 m0, s76, 0x2000
	s_add_u32 s76, s4, 0x80000
	s_addc_u32 s77, s5, 0
	s_add_i32 s78, s78, s24
	global_load_lds_dwordx4 v128, s[4:5]
	s_mov_b32 m0, s78
	ds_read_b128 v[196:199], v143 offset:20480
	global_load_lds_dwordx4 v160, s[76:77]
	s_add_i32 m0, s78, 0x2000
	ds_read_b128 v[222:225], v143 offset:21504
	global_load_lds_dwordx4 v128, s[76:77]
	s_mov_b32 m0, s51
	ds_read_b128 v[226:229], v143 offset:22528
	global_load_lds_dwordx4 v132, s[52:53]
	s_mov_b32 m0, s55
	ds_read_b128 v[230:233], v143 offset:23552
	global_load_lds_dwordx4 v130, s[52:53]
	s_add_u32 s98, s52, 0x80
	s_addc_u32 s99, s53, 0


; #define PG8_STAGE(bufoff, gbase, voff) do { _Pragma("unroll") for (int _i = 0; _i < 2; ++_i) \
;         __builtin_amdgcn_global_load_lds((const unsigned*)((const char*)(gbase) + (voff)[_i]), (PG8_LAS unsigned*)(lds + (bufoff) + ldsw + _i * 8192), 16, 0, 0); } while (0)
; #define PG8_LDA(dst, b, h) do { _Pragma("unroll") for (int m = 0; m < 4; ++m) _Pragma("unroll") for (int k = 0; k < 2; ++k) dst[m][k] = *(const PG8_LAS bf16x8*)(lds + PG8_SA(b, h) + aoff + m * 2048 + k * 1024); } while (0)
; #define PG8_LDB(dst, b, h) do { _Pragma("unroll") for (int n = 0; n < 2; ++n) _Pragma("unroll") for (int k = 0; k < 2; ++k) dst[n][k] = *(const PG8_LAS bf16x8*)(lds + PG8_SB(b, h) + boff + n * 2048 + k * 1024); } while (0)
; #define PG8_MMA(ai, bj, At, Bt) do { __builtin_amdgcn_s_setprio(1); _Pragma("unroll") for (int m = 0; m < 4; ++m) _Pragma("unroll") for (int n = 0; n < 2; ++n) _Pragma("unroll") for (int k = 0; k < 2; ++k) \
;         acc[ai][bj][m][n] = __builtin_amdgcn_mfma_f32_16x16x32_bf16(Bt[n][k], At[m][k], acc[ai][bj][m][n], 0, 0, 0); __builtin_amdgcn_s_setprio(0); } while (0)
; #define PG8_WAIT_V(n) asm volatile("s_waitcnt vmcnt(" #n ")" ::: "memory")
; #define PG8_WAIT_L(n) asm volatile("s_waitcnt lgkmcnt(" #n ")" ::: "memory")
; #define PG8_BAR __builtin_amdgcn_s_barrier()
; #define PG8_SCHED __builtin_amdgcn_sched_barrier(0)
; template <class Epi, class Sched, bool ALIGN_EPI = false, bool SP2 = false>
; __device__ __forceinline__ void gemm_phase(PG8_LAS unsigned char* lds, const Gemm g, const Sched& S, const Epi& E) {
;     ...
;             PG8_WAIT_V(8); PG8_WAIT_L(0); PG8_BAR; PG8_MMA(1, 0, At, B0); PG8_MMA(1, 1, At, B1); PG8_BAR; PG8_SCHED;
;             PG8_LDB(B0, 1, 0); PG8_LDB(B1, 1, 1); PG8_SCHED; PG8_LDA(At, 1, 0); PG8_STAGE(PG8_SA(0, 1), a2 + hstep, voffA);
	s_waitcnt vmcnt(8)
	s_waitcnt lgkmcnt(0)
	s_barrier
	s_waitcnt lgkmcnt(0)
	v_mfma_f32_16x16x32_bf16 v[60:63], v[144:147], v[180:183], v[60:63]
	v_mfma_f32_16x16x32_bf16 v[52:55], v[152:155], v[180:183], v[52:55]
	v_mfma_f32_16x16x32_bf16 v[44:47], v[144:147], v[188:191], v[44:47]
	v_mfma_f32_16x16x32_bf16 v[36:39], v[152:155], v[188:191], v[36:39]
	v_mfma_f32_16x16x32_bf16 v[28:31], v[144:147], v[196:199], v[28:31]
	v_mfma_f32_16x16x32_bf16 v[20:23], v[152:155], v[196:199], v[20:23]
	v_mfma_f32_16x16x32_bf16 v[12:15], v[144:147], v[226:229], v[12:15]
	v_mfma_f32_16x16x32_bf16 v[4:7], v[152:155], v[226:229], v[4:7]
	v_mfma_f32_16x16x32_bf16 v[60:63], v[148:151], v[184:187], v[60:63]
	v_mfma_f32_16x16x32_bf16 v[52:55], v[156:159], v[184:187], v[52:55]
	v_mfma_f32_16x16x32_bf16 v[44:47], v[148:151], v[192:195], v[44:47]
	v_mfma_f32_16x16x32_bf16 v[36:39], v[156:159], v[192:195], v[36:39]
	v_mfma_f32_16x16x32_bf16 v[28:31], v[148:151], v[222:225], v[28:31]
	v_mfma_f32_16x16x32_bf16 v[20:23], v[156:159], v[222:225], v[20:23]
	v_mfma_f32_16x16x32_bf16 v[12:15], v[148:151], v[230:233], v[12:15]
	v_mfma_f32_16x16x32_bf16 v[4:7], v[156:159], v[230:233], v[4:7]
	v_mfma_f32_16x16x32_bf16 v[56:59], v[164:167], v[180:183], v[56:59]
	v_mfma_f32_16x16x32_bf16 v[48:51], v[172:175], v[180:183], v[48:51]
	v_mfma_f32_16x16x32_bf16 v[40:43], v[164:167], v[188:191], v[40:43]
	v_mfma_f32_16x16x32_bf16 v[32:35], v[172:175], v[188:191], v[32:35]
	v_mfma_f32_16x16x32_bf16 v[24:27], v[164:167], v[196:199], v[24:27]
	v_mfma_f32_16x16x32_bf16 v[16:19], v[172:175], v[196:199], v[16:19]
	v_mfma_f32_16x16x32_bf16 v[8:11], v[164:167], v[226:229], v[8:11]
	v_mfma_f32_16x16x32_bf16 v[0:3], v[172:175], v[226:229], v[0:3]
	v_mfma_f32_16x16x32_bf16 v[56:59], v[168:171], v[184:187], v[56:59]
	v_mfma_f32_16x16x32_bf16 v[48:51], v[176:179], v[184:187], v[48:51]
	v_mfma_f32_16x16x32_bf16 v[40:43], v[168:171], v[192:195], v[40:43]
	v_mfma_f32_16x16x32_bf16 v[32:35], v[176:179], v[192:195], v[32:35]
	v_mfma_f32_16x16x32_bf16 v[24:27], v[168:171], v[222:225], v[24:27]
	v_mfma_f32_16x16x32_bf16 v[16:19], v[176:179], v[222:225], v[16:19]
	v_mfma_f32_16x16x32_bf16 v[8:11], v[168:171], v[230:233], v[8:11]
	v_mfma_f32_16x16x32_bf16 v[0:3], v[176:179], v[230:233], v[0:3]
	s_barrier
	s_add_i32 s76, 0, 0x18000
	s_add_i32 s77, 0, 0x1c000
	ds_read_b128 v[144:147], v200 offset:32768
	ds_read_b128 v[148:151], v200 offset:33792
	ds_read_b128 v[152:155], v200 offset:34816
	ds_read_b128 v[156:159], v200 offset:35840
	ds_read_b128 v[164:167], v200 offset:49152
	ds_read_b128 v[168:171], v200 offset:50176
	ds_read_b128 v[172:175], v200 offset:51200
	ds_read_b128 v[176:179], v200 offset:52224
	s_add_u32 s52, s52, 0x80000
	s_addc_u32 s53, s53, 0
	s_mov_b32 m0, s56
	ds_read_b128 v[180:183], v143 offset:32768
	ds_read_b128 v[184:187], v143 offset:33792
	ds_read_b128 v[188:191], v143 offset:34816
	ds_read_b128 v[192:195], v143 offset:35840
	ds_read_b128 v[196:199], v143 offset:36864
	ds_read_b128 v[222:225], v143 offset:37888
	ds_read_b128 v[226:229], v143 offset:38912
	global_load_lds_dwordx4 v132, s[52:53]
	s_mov_b32 m0, s57
	ds_read_b128 v[230:233], v143 offset:39936
	global_load_lds_dwordx4 v130, s[52:53]

; #define PG8_STAGE(bufoff, gbase, voff) do { _Pragma("unroll") for (int _i = 0; _i < 2; ++_i) \
;         __builtin_amdgcn_global_load_lds((const unsigned*)((const char*)(gbase) + (voff)[_i]), (PG8_LAS unsigned*)(lds + (bufoff) + ldsw + _i * 8192), 16, 0, 0); } while (0)
; #define PG8_LDA(dst, b, h) do { _Pragma("unroll") for (int m = 0; m < 4; ++m) _Pragma("unroll") for (int k = 0; k < 2; ++k) dst[m][k] = *(const PG8_LAS bf16x8*)(lds + PG8_SA(b, h) + aoff + m * 2048 + k * 1024); } while (0)
; #define PG8_MMA(ai, bj, At, Bt) do { __builtin_amdgcn_s_setprio(1); _Pragma("unroll") for (int m = 0; m < 4; ++m) _Pragma("unroll") for (int n = 0; n < 2; ++n) _Pragma("unroll") for (int k = 0; k < 2; ++k) \
;         acc[ai][bj][m][n] = __builtin_amdgcn_mfma_f32_16x16x32_bf16(Bt[n][k], At[m][k], acc[ai][bj][m][n], 0, 0, 0); __builtin_amdgcn_s_setprio(0); } while (0)
; #define PG8_WAIT_V(n) asm volatile("s_waitcnt vmcnt(" #n ")" ::: "memory")
; #define PG8_WAIT_L(n) asm volatile("s_waitcnt lgkmcnt(" #n ")" ::: "memory")
; #define PG8_BAR __builtin_amdgcn_s_barrier()
; #define PG8_SCHED __builtin_amdgcn_sched_barrier(0)
; template <class Epi, class Sched, bool ALIGN_EPI = false, bool SP2 = false>
; __device__ __forceinline__ void gemm_phase(PG8_LAS unsigned char* lds, const Gemm g, const Sched& S, const Epi& E) {
;     ...
;             PG8_WAIT_V(8); PG8_WAIT_L(0); PG8_BAR; PG8_MMA(0, 0, At, B0); PG8_MMA(0, 1, At, B1); PG8_BAR; PG8_SCHED;
;             PG8_LDA(At, 1, 1); PG8_STAGE(PG8_SB(1, 0), b3, voffB); PG8_STAGE(PG8_SB(1, 1), b3 + hstep, voffB); PG8_STAGE(PG8_SA(1, 0), a3, voffA);
	s_waitcnt vmcnt(8)
	s_waitcnt lgkmcnt(0)
	s_barrier
	s_waitcnt lgkmcnt(0)
	v_mfma_f32_16x16x32_bf16 v[124:127], v[144:147], v[180:183], v[124:127]
	v_mfma_f32_16x16x32_bf16 v[116:119], v[152:155], v[180:183], v[116:119]
	v_mfma_f32_16x16x32_bf16 v[108:111], v[144:147], v[188:191], v[108:111]
	v_mfma_f32_16x16x32_bf16 v[100:103], v[152:155], v[188:191], v[100:103]
	v_mfma_f32_16x16x32_bf16 v[92:95], v[144:147], v[196:199], v[92:95]
	v_mfma_f32_16x16x32_bf16 v[84:87], v[152:155], v[196:199], v[84:87]
	v_mfma_f32_16x16x32_bf16 v[76:79], v[144:147], v[226:229], v[76:79]
	v_mfma_f32_16x16x32_bf16 v[68:71], v[152:155], v[226:229], v[68:71]
	v_mfma_f32_16x16x32_bf16 v[124:127], v[148:151], v[184:187], v[124:127]
	v_mfma_f32_16x16x32_bf16 v[116:119], v[156:159], v[184:187], v[116:119]
	v_mfma_f32_16x16x32_bf16 v[108:111], v[148:151], v[192:195], v[108:111]
	v_mfma_f32_16x16x32_bf16 v[100:103], v[156:159], v[192:195], v[100:103]
	v_mfma_f32_16x16x32_bf16 v[92:95], v[148:151], v[222:225], v[92:95]
	v_mfma_f32_16x16x32_bf16 v[84:87], v[156:159], v[222:225], v[84:87]
	v_mfma_f32_16x16x32_bf16 v[76:79], v[148:151], v[230:233], v[76:79]
	v_mfma_f32_16x16x32_bf16 v[68:71], v[156:159], v[230:233], v[68:71]
	v_mfma_f32_16x16x32_bf16 v[120:123], v[164:167], v[180:183], v[120:123]
	v_mfma_f32_16x16x32_bf16 v[112:115], v[172:175], v[180:183], v[112:115]
	v_mfma_f32_16x16x32_bf16 v[104:107], v[164:167], v[188:191], v[104:107]
	v_mfma_f32_16x16x32_bf16 v[96:99], v[172:175], v[188:191], v[96:99]
	v_mfma_f32_16x16x32_bf16 v[88:91], v[164:167], v[196:199], v[88:91]
	v_mfma_f32_16x16x32_bf16 v[80:83], v[172:175], v[196:199], v[80:83]
	v_mfma_f32_16x16x32_bf16 v[72:75], v[164:167], v[226:229], v[72:75]
	v_mfma_f32_16x16x32_bf16 v[64:67], v[172:175], v[226:229], v[64:67]
	v_mfma_f32_16x16x32_bf16 v[120:123], v[168:171], v[184:187], v[120:123]
	v_mfma_f32_16x16x32_bf16 v[112:115], v[176:179], v[184:187], v[112:115]
	v_mfma_f32_16x16x32_bf16 v[104:107], v[168:171], v[192:195], v[104:107]
	v_mfma_f32_16x16x32_bf16 v[96:99], v[176:179], v[192:195], v[96:99]
	v_mfma_f32_16x16x32_bf16 v[88:91], v[168:171], v[222:225], v[88:91]
	v_mfma_f32_16x16x32_bf16 v[80:83], v[176:179], v[222:225], v[80:83]
	v_mfma_f32_16x16x32_bf16 v[72:75], v[168:171], v[230:233], v[72:75]
	v_mfma_f32_16x16x32_bf16 v[64:67], v[176:179], v[230:233], v[64:67]
	s_barrier
	s_add_i32 s52, s76, s24
	s_mov_b32 m0, s52
	ds_read_b128 v[180:183], v143 offset:49152
	ds_read_b128 v[184:187], v143 offset:50176
	ds_read_b128 v[188:191], v143 offset:51200
	ds_read_b128 v[192:195], v143 offset:52224
	s_add_u32 s4, s4, 0x80
	s_addc_u32 s5, s5, 0
	global_load_lds_dwordx4 v160, s[4:5]
	s_add_i32 m0, s52, 0x2000
	s_add_i32 s52, s77, s24
	global_load_lds_dwordx4 v128, s[4:5]
	s_add_u32 s4, s4, 0x80000
	s_addc_u32 s5, s5, 0
	s_mov_b32 m0, s52
	ds_read_b128 v[196:199], v143 offset:53248
	global_load_lds_dwordx4 v160, s[4:5]
	s_add_i32 m0, s52, 0x2000
	ds_read_b128 v[222:225], v143 offset:54272
	global_load_lds_dwordx4 v128, s[4:5]
	s_mov_b32 m0, s58
	ds_read_b128 v[226:229], v143 offset:55296
	global_load_lds_dwordx4 v132, s[98:99]
	s_mov_b32 m0, s59
	ds_read_b128 v[230:233], v143 offset:56320
	global_load_lds_dwordx4 v130, s[98:99]


; #define PG8_STAGE(bufoff, gbase, voff) do { _Pragma("unroll") for (int _i = 0; _i < 2; ++_i) \
;         __builtin_amdgcn_global_load_lds((const unsigned*)((const char*)(gbase) + (voff)[_i]), (PG8_LAS unsigned*)(lds + (bufoff) + ldsw + _i * 8192), 16, 0, 0); } while (0)
; #define PG8_LDA(dst, b, h) do { _Pragma("unroll") for (int m = 0; m < 4; ++m) _Pragma("unroll") for (int k = 0; k < 2; ++k) dst[m][k] = *(const PG8_LAS bf16x8*)(lds + PG8_SA(b, h) + aoff + m * 2048 + k * 1024); } while (0)
; #define PG8_LDB(dst, b, h) do { _Pragma("unroll") for (int n = 0; n < 2; ++n) _Pragma("unroll") for (int k = 0; k < 2; ++k) dst[n][k] = *(const PG8_LAS bf16x8*)(lds + PG8_SB(b, h) + boff + n * 2048 + k * 1024); } while (0)
; template <class Epi, class Sched, bool ALIGN_EPI = false, bool SP2 = false>
; __device__ __forceinline__ void gemm_phase(PG8_LAS unsigned char* lds, const Gemm g, const Sched& S, const Epi& E) {
;     ...
;             PG8_WAIT_V(8); PG8_WAIT_L(0); PG8_BAR; PG8_MMA(1, 0, At, B0); PG8_MMA(1, 1, At, B1); PG8_BAR; PG8_SCHED;
;             } else {
;             PG8_LDB(B0, 0, 0); PG8_SCHED; PG8_LDA(At, 0, 0); PG8_STAGE(PG8_SA(1, 1), a1 + hstep, voffA);
;             PG8_WAIT_L(8); PG8_BAR; PG8_WAIT_L(0); PG8_MMA(0, 0, At, B0); PG8_BAR; PG8_SCHED;
;             PG8_LDB(B1, 0, 1); PG8_STAGE(PG8_SB(0, 0), b2, voffB);
;             PG8_BAR; PG8_WAIT_L(0); PG8_MMA(0, 1, At, B1); PG8_BAR;
;             PG8_LDA(At, 0, 1); PG8_STAGE(PG8_SA(0, 0), a2, voffA);
;             PG8_BAR; PG8_WAIT_L(0); PG8_MMA(1, 0, At, B0); PG8_BAR; PG8_SCHED;
;             PG8_STAGE(PG8_SB(0, 1), b2 + hstep, voffB);
;             PG8_WAIT_V(6); PG8_BAR; PG8_MMA(1, 1, At, B1); PG8_BAR;
;             PG8_LDB(B0, 1, 0); PG8_SCHED; PG8_LDA(At, 1, 0); PG8_STAGE(PG8_SA(0, 1), a2 + hstep, voffA);
;             PG8_WAIT_L(8); PG8_BAR; PG8_WAIT_L(0); PG8_MMA(0, 0, At, B0); PG8_BAR; PG8_SCHED;
;             PG8_LDB(B1, 1, 1); PG8_STAGE(PG8_SB(1, 0), b3, voffB);
;             PG8_BAR; PG8_WAIT_L(0); PG8_MMA(0, 1, At, B1); PG8_BAR;
;             PG8_LDA(At, 1, 1); PG8_STAGE(PG8_SA(1, 0), a3, voffA);
;             PG8_BAR; PG8_WAIT_L(0); PG8_MMA(1, 0, At, B0); PG8_BAR; PG8_SCHED;
;             PG8_STAGE(PG8_SB(1, 1), b3 + hstep, voffB);
;             PG8_WAIT_V(6); PG8_BAR; PG8_MMA(1, 1, At, B1); PG8_BAR;
;             }
;         }
;         if constexpr (ALIGN_EPI) { if (wr == 0) PG8_BAR; }
	s_waitcnt vmcnt(8)
	s_waitcnt lgkmcnt(0)
	s_barrier
	s_waitcnt lgkmcnt(0)
	v_mfma_f32_16x16x32_bf16 v[60:63], v[144:147], v[180:183], v[60:63]
	v_mfma_f32_16x16x32_bf16 v[52:55], v[152:155], v[180:183], v[52:55]
	v_mfma_f32_16x16x32_bf16 v[44:47], v[144:147], v[188:191], v[44:47]
	v_mfma_f32_16x16x32_bf16 v[36:39], v[152:155], v[188:191], v[36:39]
	v_mfma_f32_16x16x32_bf16 v[28:31], v[144:147], v[196:199], v[28:31]
	v_mfma_f32_16x16x32_bf16 v[20:23], v[152:155], v[196:199], v[20:23]
	v_mfma_f32_16x16x32_bf16 v[12:15], v[144:147], v[226:229], v[12:15]
	v_mfma_f32_16x16x32_bf16 v[4:7], v[152:155], v[226:229], v[4:7]
	v_mfma_f32_16x16x32_bf16 v[60:63], v[148:151], v[184:187], v[60:63]
	v_mfma_f32_16x16x32_bf16 v[52:55], v[156:159], v[184:187], v[52:55]
	v_mfma_f32_16x16x32_bf16 v[44:47], v[148:151], v[192:195], v[44:47]
	v_mfma_f32_16x16x32_bf16 v[36:39], v[156:159], v[192:195], v[36:39]
	v_mfma_f32_16x16x32_bf16 v[28:31], v[148:151], v[222:225], v[28:31]
	v_mfma_f32_16x16x32_bf16 v[20:23], v[156:159], v[222:225], v[20:23]
	v_mfma_f32_16x16x32_bf16 v[12:15], v[148:151], v[230:233], v[12:15]
	v_mfma_f32_16x16x32_bf16 v[4:7], v[156:159], v[230:233], v[4:7]
	v_mfma_f32_16x16x32_bf16 v[56:59], v[164:167], v[180:183], v[56:59]
	v_mfma_f32_16x16x32_bf16 v[48:51], v[172:175], v[180:183], v[48:51]
	v_mfma_f32_16x16x32_bf16 v[40:43], v[164:167], v[188:191], v[40:43]
	v_mfma_f32_16x16x32_bf16 v[32:35], v[172:175], v[188:191], v[32:35]
	v_mfma_f32_16x16x32_bf16 v[24:27], v[164:167], v[196:199], v[24:27]
	v_mfma_f32_16x16x32_bf16 v[16:19], v[172:175], v[196:199], v[16:19]
	v_mfma_f32_16x16x32_bf16 v[8:11], v[164:167], v[226:229], v[8:11]
	v_mfma_f32_16x16x32_bf16 v[0:3], v[172:175], v[226:229], v[0:3]
	v_mfma_f32_16x16x32_bf16 v[56:59], v[168:171], v[184:187], v[56:59]
	v_mfma_f32_16x16x32_bf16 v[48:51], v[176:179], v[184:187], v[48:51]
	v_mfma_f32_16x16x32_bf16 v[40:43], v[168:171], v[192:195], v[40:43]
	v_mfma_f32_16x16x32_bf16 v[32:35], v[176:179], v[192:195], v[32:35]
	v_mfma_f32_16x16x32_bf16 v[24:27], v[168:171], v[222:225], v[24:27]
	v_mfma_f32_16x16x32_bf16 v[16:19], v[176:179], v[222:225], v[16:19]
	v_mfma_f32_16x16x32_bf16 v[8:11], v[168:171], v[230:233], v[8:11]
	v_mfma_f32_16x16x32_bf16 v[0:3], v[176:179], v[230:233], v[0:3]
	s_barrier
	s_add_i32 s75, s75, 2
	s_add_u32 s70, s70, 0x100
	s_addc_u32 s71, s71, 0
	s_add_u32 s73, s73, 0x100
	s_addc_u32 s74, s74, 0
	s_cmp_gt_u32 s75, 29
	s_cbranch_scc0 .LBB0_849
	s_and_b64 vcc, exec, s[8:9]
	s_cbranch_vccz .LBB0_852
	s_barrier
